# v082 + paired RMSNorm reductions + GEMM load blocks with LDS-DMA first and merged waits (combination of individually neutral variants)
# baseline (speedup 1.0000x reference)
; #define PG8_STAGE(bufoff, gbase, voff) do { _Pragma("unroll") for (int _i = 0; _i < 2; ++_i) \
;         __builtin_amdgcn_global_load_lds((const gunsigned*)((const gchar*)(gbase) + (voff)[_i]), (LAS unsigned*)(lds + (bufoff) + ldsw + _i * 8192), 16, 0, 0); } while (0)
; #define PG8_LDA(dst, b, h) do { _Pragma("unroll") for (int m = 0; m < 4; ++m) _Pragma("unroll") for (int k = 0; k < 2; ++k) dst[m][k] = *(const LAS bf16x8*)(lds + PG8_SA(b, h) + aoff + m * 2048 + k * 1024); } while (0)
; #define PG8_LDB(dst, b, h) do { _Pragma("unroll") for (int n = 0; n < 2; ++n) _Pragma("unroll") for (int k = 0; k < 2; ++k) dst[n][k] = *(const LAS bf16x8*)(lds + PG8_SB(b, h) + boff + n * 2048 + k * 1024); } while (0)
; #define PG8_MMA(ai, bj, At, Bt) do { __builtin_amdgcn_s_setprio(1); _Pragma("unroll") for (int m = 0; m < 4; ++m) _Pragma("unroll") for (int n = 0; n < 2; ++n) _Pragma("unroll") for (int k = 0; k < 2; ++k) \
;         acc[ai][bj][m][n] = __builtin_amdgcn_mfma_f32_16x16x32_bf16(Bt[n][k], At[m][k], acc[ai][bj][m][n], 0, 0, 0); __builtin_amdgcn_s_setprio(0); } while (0)
; #define PG8_WAIT_V(n) asm volatile("s_waitcnt vmcnt(" #n ")" ::: "memory")
; #define PG8_WAIT_L(n) asm volatile("s_waitcnt lgkmcnt(" #n ")" ::: "memory")
; #define PG8_BAR __builtin_amdgcn_s_barrier()
; #define PG8_SCHED __builtin_amdgcn_sched_barrier(0)
; template <class Epi, class Sched>
; __device__ __forceinline__ void gemm_phase(LAS unsigned char* lds, const int tid, const Gemm g, const Sched& S, const Epi& E) {
;     ...
;         for (int t = 0; t < nt; t += 2) {
;             const bool last = (t == nt - 2);
;             const gchar* a1 = cA + (size_t)(t + 1) * kstep;
;             const gchar* a2 = last ? nA : cA + (size_t)(t + 2) * kstep; const gchar* b2 = last ? nB : cB + (size_t)(t + 2) * kstep;
;             const gchar* a3 = a2 + kstep; const gchar* b3 = b2 + kstep;
;             PG8_LDB(B0, 0, 0); PG8_LDB(B1, 0, 1); PG8_SCHED; PG8_LDA(At, 0, 0); PG8_STAGE(PG8_SA(1, 1), a1 + hstep, voffA);
;             PG8_WAIT_V(8); PG8_WAIT_L(0); PG8_BAR; PG8_MMA(0, 0, At, B0); PG8_MMA(0, 1, At, B1); PG8_BAR; PG8_SCHED;
;             PG8_LDA(At, 0, 1); PG8_STAGE(PG8_SB(0, 0), b2, voffB); PG8_STAGE(PG8_SB(0, 1), b2 + hstep, voffB); PG8_STAGE(PG8_SA(0, 0), a2, voffA);
;             PG8_WAIT_V(8); PG8_WAIT_L(0); PG8_BAR; PG8_MMA(1, 0, At, B0); PG8_MMA(1, 1, At, B1); PG8_BAR; PG8_SCHED;
.LBB0_319:
	s_add_u32 vcc_lo, s10, 0x100
	s_addc_u32 vcc_hi, s11, 0
	s_add_i32 s39, 0, 0x10000
	s_cmp_eq_u32 s29, 40
	s_cselect_b32 s75, s21, vcc_hi
	s_cselect_b32 s74, s20, vcc_lo
	s_cselect_b32 s73, s1, s93
	s_cselect_b32 s72, s0, s31
	s_add_i32 s30, 0, 0x14000
	s_add_i32 m0, s46, 0xc000
	global_load_lds_dwordx4 v162, s[10:11]
	s_add_i32 m0, s46, 0xe000
	s_nop 0
	global_load_lds_dwordx4 v160, s[10:11]
	v_add_u32_e32 v142, s39, v174
	v_add_u32_e32 v168, s30, v174
	ds_read_b128 v[130:133], v142
	ds_read_b128 v[134:137], v142 offset:1024
	ds_read_b128 v[138:141], v142 offset:2048
	ds_read_b128 v[142:145], v142 offset:3072
	ds_read_b128 v[146:149], v168
	ds_read_b128 v[150:153], v168 offset:1024
	ds_read_b128 v[164:167], v168 offset:2048
	ds_read_b128 v[168:171], v168 offset:3072
	ds_read_b128 v[192:195], v190
	ds_read_b128 v[204:207], v190 offset:1024
	ds_read_b128 v[208:211], v190 offset:2048
	ds_read_b128 v[212:215], v190 offset:3072
	ds_read_b128 v[216:219], v190 offset:4096
	ds_read_b128 v[220:223], v190 offset:5120
	ds_read_b128 v[224:227], v190 offset:6144
	ds_read_b128 v[242:245], v190 offset:7168
	s_waitcnt vmcnt(8) lgkmcnt(0)
	s_setprio 1
	s_barrier
	v_mfma_f32_16x16x32_bf16 v[126:129], v[130:133], v[192:195], v[126:129]
	v_mfma_f32_16x16x32_bf16 v[122:125], v[138:141], v[192:195], v[122:125]
	v_mfma_f32_16x16x32_bf16 v[110:113], v[130:133], v[208:211], v[110:113]
	v_mfma_f32_16x16x32_bf16 v[106:109], v[138:141], v[208:211], v[106:109]
	v_mfma_f32_16x16x32_bf16 v[94:97], v[130:133], v[216:219], v[94:97]
	v_mfma_f32_16x16x32_bf16 v[90:93], v[138:141], v[216:219], v[90:93]
	v_mfma_f32_16x16x32_bf16 v[78:81], v[130:133], v[224:227], v[78:81]
	v_mfma_f32_16x16x32_bf16 v[74:77], v[138:141], v[224:227], v[74:77]
	v_mfma_f32_16x16x32_bf16 v[126:129], v[134:137], v[204:207], v[126:129]
	v_mfma_f32_16x16x32_bf16 v[122:125], v[142:145], v[204:207], v[122:125]
	v_mfma_f32_16x16x32_bf16 v[110:113], v[134:137], v[212:215], v[110:113]
	v_mfma_f32_16x16x32_bf16 v[106:109], v[142:145], v[212:215], v[106:109]
	v_mfma_f32_16x16x32_bf16 v[94:97], v[134:137], v[220:223], v[94:97]
	v_mfma_f32_16x16x32_bf16 v[90:93], v[142:145], v[220:223], v[90:93]
	v_mfma_f32_16x16x32_bf16 v[78:81], v[134:137], v[242:245], v[78:81]
	v_mfma_f32_16x16x32_bf16 v[74:77], v[142:145], v[242:245], v[74:77]
	s_setprio 0
	s_setprio 1
	v_mfma_f32_16x16x32_bf16 v[118:121], v[146:149], v[192:195], v[118:121]
	v_mfma_f32_16x16x32_bf16 v[114:117], v[164:167], v[192:195], v[114:117]
	v_mfma_f32_16x16x32_bf16 v[102:105], v[146:149], v[208:211], v[102:105]
	v_mfma_f32_16x16x32_bf16 v[98:101], v[164:167], v[208:211], v[98:101]
	v_mfma_f32_16x16x32_bf16 v[86:89], v[146:149], v[216:219], v[86:89]
	v_mfma_f32_16x16x32_bf16 v[82:85], v[164:167], v[216:219], v[82:85]
	v_mfma_f32_16x16x32_bf16 v[70:73], v[146:149], v[224:227], v[70:73]
	v_mfma_f32_16x16x32_bf16 v[66:69], v[164:167], v[224:227], v[66:69]
	v_mfma_f32_16x16x32_bf16 v[118:121], v[150:153], v[204:207], v[118:121]
	v_mfma_f32_16x16x32_bf16 v[114:117], v[168:171], v[204:207], v[114:117]
	v_mfma_f32_16x16x32_bf16 v[102:105], v[150:153], v[212:215], v[102:105]
	v_mfma_f32_16x16x32_bf16 v[98:101], v[168:171], v[212:215], v[98:101]
	v_mfma_f32_16x16x32_bf16 v[86:89], v[150:153], v[220:223], v[86:89]
	v_mfma_f32_16x16x32_bf16 v[82:85], v[168:171], v[220:223], v[82:85]
	v_mfma_f32_16x16x32_bf16 v[70:73], v[150:153], v[242:245], v[70:73]
	v_mfma_f32_16x16x32_bf16 v[66:69], v[168:171], v[242:245], v[66:69]
	s_barrier
	s_setprio 0
	s_add_i32 s10, s39, s43
	s_mov_b32 m0, s10
	global_load_lds_dwordx4 v0, s[72:73]
	s_add_i32 m0, s10, 0x2000
	s_add_u32 s10, s72, 0xb0000
	s_addc_u32 s11, s73, 0
	s_add_i32 s30, s30, s43
	global_load_lds_dwordx4 v158, s[72:73]
	s_mov_b32 m0, s30
	s_nop 0
	global_load_lds_dwordx4 v0, s[10:11]
	s_add_i32 m0, s30, 0x2000
	s_nop 0
	global_load_lds_dwordx4 v158, s[10:11]
	s_mov_b32 m0, s46
	s_nop 0
	global_load_lds_dwordx4 v154, s[74:75]
	s_mov_b32 m0, s47
	s_nop 0
	global_load_lds_dwordx4 v156, s[74:75]
	ds_read_b128 v[192:195], v190 offset:16384
	ds_read_b128 v[204:207], v190 offset:17408
	ds_read_b128 v[208:211], v190 offset:18432
	ds_read_b128 v[212:215], v190 offset:19456
	ds_read_b128 v[216:219], v190 offset:20480
	ds_read_b128 v[220:223], v190 offset:21504
	ds_read_b128 v[224:227], v190 offset:22528
	ds_read_b128 v[242:245], v190 offset:23552
	s_waitcnt vmcnt(8) lgkmcnt(0)
	s_setprio 1
	s_barrier
	v_mfma_f32_16x16x32_bf16 v[62:65], v[130:133], v[192:195], v[62:65]
	v_mfma_f32_16x16x32_bf16 v[58:61], v[138:141], v[192:195], v[58:61]
	v_mfma_f32_16x16x32_bf16 v[46:49], v[130:133], v[208:211], v[46:49]
	v_mfma_f32_16x16x32_bf16 v[42:45], v[138:141], v[208:211], v[42:45]
	v_mfma_f32_16x16x32_bf16 v[30:33], v[130:133], v[216:219], v[30:33]
	v_mfma_f32_16x16x32_bf16 v[26:29], v[138:141], v[216:219], v[26:29]
	v_mfma_f32_16x16x32_bf16 v[14:17], v[130:133], v[224:227], v[14:17]
	v_mfma_f32_16x16x32_bf16 v[10:13], v[138:141], v[224:227], v[10:13]
	v_mfma_f32_16x16x32_bf16 v[62:65], v[134:137], v[204:207], v[62:65]
	v_mfma_f32_16x16x32_bf16 v[58:61], v[142:145], v[204:207], v[58:61]
	v_mfma_f32_16x16x32_bf16 v[46:49], v[134:137], v[212:215], v[46:49]
	v_mfma_f32_16x16x32_bf16 v[42:45], v[142:145], v[212:215], v[42:45]
	v_mfma_f32_16x16x32_bf16 v[30:33], v[134:137], v[220:223], v[30:33]
	v_mfma_f32_16x16x32_bf16 v[26:29], v[142:145], v[220:223], v[26:29]
	v_mfma_f32_16x16x32_bf16 v[14:17], v[134:137], v[242:245], v[14:17]
	v_mfma_f32_16x16x32_bf16 v[10:13], v[142:145], v[242:245], v[10:13]
	s_setprio 0
	s_setprio 1
	v_mfma_f32_16x16x32_bf16 v[54:57], v[146:149], v[192:195], v[54:57]
	v_mfma_f32_16x16x32_bf16 v[50:53], v[164:167], v[192:195], v[50:53]
	v_mfma_f32_16x16x32_bf16 v[38:41], v[146:149], v[208:211], v[38:41]
	v_mfma_f32_16x16x32_bf16 v[34:37], v[164:167], v[208:211], v[34:37]
	v_mfma_f32_16x16x32_bf16 v[22:25], v[146:149], v[216:219], v[22:25]
	v_mfma_f32_16x16x32_bf16 v[18:21], v[164:167], v[216:219], v[18:21]
	v_mfma_f32_16x16x32_bf16 v[6:9], v[146:149], v[224:227], v[6:9]
	v_mfma_f32_16x16x32_bf16 v[2:5], v[164:167], v[224:227], v[2:5]
	v_mfma_f32_16x16x32_bf16 v[54:57], v[150:153], v[204:207], v[54:57]
	v_mfma_f32_16x16x32_bf16 v[50:53], v[168:171], v[204:207], v[50:53]
	v_mfma_f32_16x16x32_bf16 v[38:41], v[150:153], v[212:215], v[38:41]
	v_mfma_f32_16x16x32_bf16 v[34:37], v[168:171], v[212:215], v[34:37]
	v_mfma_f32_16x16x32_bf16 v[22:25], v[150:153], v[220:223], v[22:25]
	v_mfma_f32_16x16x32_bf16 v[18:21], v[168:171], v[220:223], v[18:21]
	v_mfma_f32_16x16x32_bf16 v[6:9], v[150:153], v[242:245], v[6:9]
	v_mfma_f32_16x16x32_bf16 v[2:5], v[168:171], v[242:245], v[2:5]
	s_barrier
; #define PG8_STAGE(bufoff, gbase, voff) do { _Pragma("unroll") for (int _i = 0; _i < 2; ++_i) \
;         __builtin_amdgcn_global_load_lds((const gunsigned*)((const gchar*)(gbase) + (voff)[_i]), (LAS unsigned*)(lds + (bufoff) + ldsw + _i * 8192), 16, 0, 0); } while (0)
; #define PG8_LDA(dst, b, h) do { _Pragma("unroll") for (int m = 0; m < 4; ++m) _Pragma("unroll") for (int k = 0; k < 2; ++k) dst[m][k] = *(const LAS bf16x8*)(lds + PG8_SA(b, h) + aoff + m * 2048 + k * 1024); } while (0)
; #define PG8_LDB(dst, b, h) do { _Pragma("unroll") for (int n = 0; n < 2; ++n) _Pragma("unroll") for (int k = 0; k < 2; ++k) dst[n][k] = *(const LAS bf16x8*)(lds + PG8_SB(b, h) + boff + n * 2048 + k * 1024); } while (0)
; #define PG8_MMA(ai, bj, At, Bt) do { __builtin_amdgcn_s_setprio(1); _Pragma("unroll") for (int m = 0; m < 4; ++m) _Pragma("unroll") for (int n = 0; n < 2; ++n) _Pragma("unroll") for (int k = 0; k < 2; ++k) \
;         acc[ai][bj][m][n] = __builtin_amdgcn_mfma_f32_16x16x32_bf16(Bt[n][k], At[m][k], acc[ai][bj][m][n], 0, 0, 0); __builtin_amdgcn_s_setprio(0); } while (0)
; #define PG8_WAIT_V(n) asm volatile("s_waitcnt vmcnt(" #n ")" ::: "memory")
; #define PG8_WAIT_L(n) asm volatile("s_waitcnt lgkmcnt(" #n ")" ::: "memory")
; #define PG8_BAR __builtin_amdgcn_s_barrier()
; #define PG8_SCHED __builtin_amdgcn_sched_barrier(0)
; template <class Epi, class Sched>
; __device__ __forceinline__ void gemm_phase(LAS unsigned char* lds, const int tid, const Gemm g, const Sched& S, const Epi& E) {
;     ...
;             PG8_LDB(B0, 1, 0); PG8_LDB(B1, 1, 1); PG8_SCHED; PG8_LDA(At, 1, 0); PG8_STAGE(PG8_SA(0, 1), a2 + hstep, voffA);
;             PG8_WAIT_V(8); PG8_WAIT_L(0); PG8_BAR; PG8_MMA(0, 0, At, B0); PG8_MMA(0, 1, At, B1); PG8_BAR; PG8_SCHED;
;             PG8_LDA(At, 1, 1); PG8_STAGE(PG8_SB(1, 0), b3, voffB); PG8_STAGE(PG8_SB(1, 1), b3 + hstep, voffB); PG8_STAGE(PG8_SA(1, 0), a3, voffA);
;             PG8_WAIT_V(8); PG8_WAIT_L(0); PG8_BAR; PG8_MMA(1, 0, At, B0); PG8_MMA(1, 1, At, B1); PG8_BAR; PG8_SCHED;
;         }
;         if (wr == 0) PG8_BAR;
	s_setprio 0
	s_add_i32 s30, 0, 0x18000
	s_add_i32 s39, 0, 0x1c000
	s_add_u32 s10, s74, 0xb0000
	s_addc_u32 s11, s75, 0
	s_mov_b32 m0, s48
	global_load_lds_dwordx4 v154, s[10:11]
	s_mov_b32 m0, s49
	s_nop 0
	global_load_lds_dwordx4 v156, s[10:11]
	v_add_u32_e32 v142, s30, v174
	v_add_u32_e32 v168, s39, v174
	ds_read_b128 v[130:133], v142
	ds_read_b128 v[134:137], v142 offset:1024
	ds_read_b128 v[138:141], v142 offset:2048
	ds_read_b128 v[142:145], v142 offset:3072
	ds_read_b128 v[146:149], v168
	ds_read_b128 v[150:153], v168 offset:1024
	ds_read_b128 v[164:167], v168 offset:2048
	ds_read_b128 v[168:171], v168 offset:3072
	ds_read_b128 v[192:195], v190 offset:32768
	ds_read_b128 v[204:207], v190 offset:33792
	ds_read_b128 v[208:211], v190 offset:34816
	ds_read_b128 v[212:215], v190 offset:35840
	ds_read_b128 v[216:219], v190 offset:36864
	ds_read_b128 v[220:223], v190 offset:37888
	ds_read_b128 v[224:227], v190 offset:38912
	ds_read_b128 v[242:245], v190 offset:39936
	s_waitcnt vmcnt(8) lgkmcnt(0)
	s_setprio 1
	s_barrier
	v_mfma_f32_16x16x32_bf16 v[126:129], v[130:133], v[192:195], v[126:129]
	v_mfma_f32_16x16x32_bf16 v[122:125], v[138:141], v[192:195], v[122:125]
	v_mfma_f32_16x16x32_bf16 v[110:113], v[130:133], v[208:211], v[110:113]
	v_mfma_f32_16x16x32_bf16 v[106:109], v[138:141], v[208:211], v[106:109]
	v_mfma_f32_16x16x32_bf16 v[94:97], v[130:133], v[216:219], v[94:97]
	v_mfma_f32_16x16x32_bf16 v[90:93], v[138:141], v[216:219], v[90:93]
	v_mfma_f32_16x16x32_bf16 v[78:81], v[130:133], v[224:227], v[78:81]
	v_mfma_f32_16x16x32_bf16 v[74:77], v[138:141], v[224:227], v[74:77]
	v_mfma_f32_16x16x32_bf16 v[126:129], v[134:137], v[204:207], v[126:129]
	v_mfma_f32_16x16x32_bf16 v[122:125], v[142:145], v[204:207], v[122:125]
	v_mfma_f32_16x16x32_bf16 v[110:113], v[134:137], v[212:215], v[110:113]
	v_mfma_f32_16x16x32_bf16 v[106:109], v[142:145], v[212:215], v[106:109]
	v_mfma_f32_16x16x32_bf16 v[94:97], v[134:137], v[220:223], v[94:97]
	v_mfma_f32_16x16x32_bf16 v[90:93], v[142:145], v[220:223], v[90:93]
	v_mfma_f32_16x16x32_bf16 v[78:81], v[134:137], v[242:245], v[78:81]
	v_mfma_f32_16x16x32_bf16 v[74:77], v[142:145], v[242:245], v[74:77]
	s_setprio 0
	s_setprio 1
	v_mfma_f32_16x16x32_bf16 v[118:121], v[146:149], v[192:195], v[118:121]
	v_mfma_f32_16x16x32_bf16 v[114:117], v[164:167], v[192:195], v[114:117]
	v_mfma_f32_16x16x32_bf16 v[102:105], v[146:149], v[208:211], v[102:105]
	v_mfma_f32_16x16x32_bf16 v[98:101], v[164:167], v[208:211], v[98:101]
	v_mfma_f32_16x16x32_bf16 v[86:89], v[146:149], v[216:219], v[86:89]
	v_mfma_f32_16x16x32_bf16 v[82:85], v[164:167], v[216:219], v[82:85]
	v_mfma_f32_16x16x32_bf16 v[70:73], v[146:149], v[224:227], v[70:73]
	v_mfma_f32_16x16x32_bf16 v[66:69], v[164:167], v[224:227], v[66:69]
	v_mfma_f32_16x16x32_bf16 v[118:121], v[150:153], v[204:207], v[118:121]
	v_mfma_f32_16x16x32_bf16 v[114:117], v[168:171], v[204:207], v[114:117]
	v_mfma_f32_16x16x32_bf16 v[102:105], v[150:153], v[212:215], v[102:105]
	v_mfma_f32_16x16x32_bf16 v[98:101], v[168:171], v[212:215], v[98:101]
	v_mfma_f32_16x16x32_bf16 v[86:89], v[150:153], v[220:223], v[86:89]
	v_mfma_f32_16x16x32_bf16 v[82:85], v[168:171], v[220:223], v[82:85]
	v_mfma_f32_16x16x32_bf16 v[70:73], v[150:153], v[242:245], v[70:73]
	v_mfma_f32_16x16x32_bf16 v[66:69], v[168:171], v[242:245], v[66:69]
	s_barrier
	s_setprio 0
	s_add_i32 s10, s30, s43
	s_mov_b32 m0, s10
	ds_read_b128 v[192:195], v190 offset:49152
	global_load_lds_dwordx4 v201, s[72:73]
	s_add_i32 m0, s10, 0x2000
	s_add_u32 s10, s72, 0xb0080
	s_addc_u32 s11, s73, 0
	s_add_i32 s30, s39, s43
	global_load_lds_dwordx4 v247, s[72:73]
	s_mov_b32 m0, s30
	s_nop 0
	global_load_lds_dwordx4 v0, s[10:11]
	s_add_i32 m0, s30, 0x2000
	s_nop 0
	global_load_lds_dwordx4 v158, s[10:11]
	s_mov_b32 m0, s53
	s_nop 0
	global_load_lds_dwordx4 v249, s[74:75]
	s_mov_b32 m0, s54
	s_nop 0
	global_load_lds_dwordx4 v251, s[74:75]
	ds_read_b128 v[204:207], v190 offset:50176
	ds_read_b128 v[208:211], v190 offset:51200
	ds_read_b128 v[212:215], v190 offset:52224
	ds_read_b128 v[216:219], v190 offset:53248
	ds_read_b128 v[220:223], v190 offset:54272
	ds_read_b128 v[224:227], v190 offset:55296
	ds_read_b128 v[242:245], v190 offset:56320
	s_waitcnt vmcnt(8) lgkmcnt(0)
	s_setprio 1
	s_barrier
	v_mfma_f32_16x16x32_bf16 v[62:65], v[130:133], v[192:195], v[62:65]
	v_mfma_f32_16x16x32_bf16 v[58:61], v[138:141], v[192:195], v[58:61]
	v_mfma_f32_16x16x32_bf16 v[46:49], v[130:133], v[208:211], v[46:49]
	v_mfma_f32_16x16x32_bf16 v[42:45], v[138:141], v[208:211], v[42:45]
	v_mfma_f32_16x16x32_bf16 v[30:33], v[130:133], v[216:219], v[30:33]
	v_mfma_f32_16x16x32_bf16 v[26:29], v[138:141], v[216:219], v[26:29]
	v_mfma_f32_16x16x32_bf16 v[14:17], v[130:133], v[224:227], v[14:17]
	v_mfma_f32_16x16x32_bf16 v[10:13], v[138:141], v[224:227], v[10:13]
	v_mfma_f32_16x16x32_bf16 v[62:65], v[134:137], v[204:207], v[62:65]
	v_mfma_f32_16x16x32_bf16 v[58:61], v[142:145], v[204:207], v[58:61]
	v_mfma_f32_16x16x32_bf16 v[46:49], v[134:137], v[212:215], v[46:49]
	v_mfma_f32_16x16x32_bf16 v[42:45], v[142:145], v[212:215], v[42:45]
	v_mfma_f32_16x16x32_bf16 v[30:33], v[134:137], v[220:223], v[30:33]
	v_mfma_f32_16x16x32_bf16 v[26:29], v[142:145], v[220:223], v[26:29]
	v_mfma_f32_16x16x32_bf16 v[14:17], v[134:137], v[242:245], v[14:17]
	v_mfma_f32_16x16x32_bf16 v[10:13], v[142:145], v[242:245], v[10:13]
	s_setprio 0
	s_setprio 1
	v_mfma_f32_16x16x32_bf16 v[54:57], v[146:149], v[192:195], v[54:57]
	v_mfma_f32_16x16x32_bf16 v[50:53], v[164:167], v[192:195], v[50:53]
	v_mfma_f32_16x16x32_bf16 v[38:41], v[146:149], v[208:211], v[38:41]
	v_mfma_f32_16x16x32_bf16 v[34:37], v[164:167], v[208:211], v[34:37]
	v_mfma_f32_16x16x32_bf16 v[22:25], v[146:149], v[216:219], v[22:25]
	v_mfma_f32_16x16x32_bf16 v[18:21], v[164:167], v[216:219], v[18:21]
	v_mfma_f32_16x16x32_bf16 v[6:9], v[146:149], v[224:227], v[6:9]
	v_mfma_f32_16x16x32_bf16 v[2:5], v[164:167], v[224:227], v[2:5]
	v_mfma_f32_16x16x32_bf16 v[54:57], v[150:153], v[204:207], v[54:57]
	v_mfma_f32_16x16x32_bf16 v[50:53], v[168:171], v[204:207], v[50:53]
	v_mfma_f32_16x16x32_bf16 v[38:41], v[150:153], v[212:215], v[38:41]
	v_mfma_f32_16x16x32_bf16 v[34:37], v[168:171], v[212:215], v[34:37]
	v_mfma_f32_16x16x32_bf16 v[22:25], v[150:153], v[220:223], v[22:25]
	v_mfma_f32_16x16x32_bf16 v[18:21], v[168:171], v[220:223], v[18:21]
	v_mfma_f32_16x16x32_bf16 v[6:9], v[150:153], v[242:245], v[6:9]
	v_mfma_f32_16x16x32_bf16 v[2:5], v[168:171], v[242:245], v[2:5]
	s_barrier
	s_setprio 0
	s_add_i32 s29, s29, 2
	s_add_u32 s31, s31, 0x100
	s_addc_u32 s93, s93, 0
	s_cmp_gt_u32 s29, 41
	s_mov_b64 s[10:11], vcc
	s_cbranch_scc0 .LBB0_319
	s_and_b64 vcc, exec, s[16:17]
	s_cbranch_vccz .LBB0_322
	s_barrier

; #define PG8_STAGE(bufoff, gbase, voff) do { _Pragma("unroll") for (int _i = 0; _i < 2; ++_i) \
;         __builtin_amdgcn_global_load_lds((const gunsigned*)((const gchar*)(gbase) + (voff)[_i]), (LAS unsigned*)(lds + (bufoff) + ldsw + _i * 8192), 16, 0, 0); } while (0)
; #define PG8_LDA(dst, b, h) do { _Pragma("unroll") for (int m = 0; m < 4; ++m) _Pragma("unroll") for (int k = 0; k < 2; ++k) dst[m][k] = *(const LAS bf16x8*)(lds + PG8_SA(b, h) + aoff + m * 2048 + k * 1024); } while (0)
; #define PG8_LDB(dst, b, h) do { _Pragma("unroll") for (int n = 0; n < 2; ++n) _Pragma("unroll") for (int k = 0; k < 2; ++k) dst[n][k] = *(const LAS bf16x8*)(lds + PG8_SB(b, h) + boff + n * 2048 + k * 1024); } while (0)
; #define PG8_MMA(ai, bj, At, Bt) do { __builtin_amdgcn_s_setprio(1); _Pragma("unroll") for (int m = 0; m < 4; ++m) _Pragma("unroll") for (int n = 0; n < 2; ++n) _Pragma("unroll") for (int k = 0; k < 2; ++k) \
;         acc[ai][bj][m][n] = __builtin_amdgcn_mfma_f32_16x16x32_bf16(Bt[n][k], At[m][k], acc[ai][bj][m][n], 0, 0, 0); __builtin_amdgcn_s_setprio(0); } while (0)
; #define PG8_WAIT_V(n) asm volatile("s_waitcnt vmcnt(" #n ")" ::: "memory")
; #define PG8_WAIT_L(n) asm volatile("s_waitcnt lgkmcnt(" #n ")" ::: "memory")
; #define PG8_BAR __builtin_amdgcn_s_barrier()
; #define PG8_SCHED __builtin_amdgcn_sched_barrier(0)
; template <class Epi, class Sched>
; __device__ __forceinline__ void gemm_phase(LAS unsigned char* lds, const int tid, const Gemm g, const Sched& S, const Epi& E) {
;     ...
;         for (int t = 0; t < nt; t += 2) {
;             const bool last = (t == nt - 2);
;             const gchar* a1 = cA + (size_t)(t + 1) * kstep;
;             const gchar* a2 = last ? nA : cA + (size_t)(t + 2) * kstep; const gchar* b2 = last ? nB : cB + (size_t)(t + 2) * kstep;
;             const gchar* a3 = a2 + kstep; const gchar* b3 = b2 + kstep;
;             PG8_LDB(B0, 0, 0); PG8_LDB(B1, 0, 1); PG8_SCHED; PG8_LDA(At, 0, 0); PG8_STAGE(PG8_SA(1, 1), a1 + hstep, voffA);
;             PG8_WAIT_V(8); PG8_WAIT_L(0); PG8_BAR; PG8_MMA(0, 0, At, B0); PG8_MMA(0, 1, At, B1); PG8_BAR; PG8_SCHED;
;             PG8_LDA(At, 0, 1); PG8_STAGE(PG8_SB(0, 0), b2, voffB); PG8_STAGE(PG8_SB(0, 1), b2 + hstep, voffB); PG8_STAGE(PG8_SA(0, 0), a2, voffA);
;             PG8_WAIT_V(8); PG8_WAIT_L(0); PG8_BAR; PG8_MMA(1, 0, At, B0); PG8_MMA(1, 1, At, B1); PG8_BAR; PG8_SCHED;
.LBB0_369:
	s_add_u32 s20, s16, 0xfffc0080
	s_addc_u32 s21, s17, -1
	s_add_i32 s29, 0, 0x10000
	s_cmp_eq_u32 s31, 12
	s_cselect_b32 s57, s11, s21
	s_cselect_b32 s56, s12, s20
	s_cselect_b32 s21, s9, s24
	s_cselect_b32 s20, s15, s23
	s_add_i32 s30, 0, 0x14000
	s_add_i32 m0, s73, 0xc000
	global_load_lds_dwordx4 v138, s[16:17]
	s_add_i32 m0, s73, 0xe000
	s_nop 0
	global_load_lds_dwordx4 v136, s[16:17]
	v_add_u32_e32 v140, s29, v145
	ds_read_b128 v[146:149], v140
	ds_read_b128 v[156:159], v140 offset:1024
	ds_read_b128 v[160:163], v140 offset:2048
	ds_read_b128 v[164:167], v140 offset:3072
	v_add_u32_e32 v140, s30, v145
	ds_read_b128 v[168:171], v140
	ds_read_b128 v[172:175], v140 offset:1024
	ds_read_b128 v[176:179], v140 offset:2048
	ds_read_b128 v[180:183], v140 offset:3072
	ds_read_b128 v[184:187], v155
	ds_read_b128 v[188:191], v155 offset:1024
	ds_read_b128 v[192:195], v155 offset:2048
	ds_read_b128 v[204:207], v155 offset:3072
	ds_read_b128 v[208:211], v155 offset:4096
	ds_read_b128 v[212:215], v155 offset:5120
	ds_read_b128 v[216:219], v155 offset:6144
	ds_read_b128 v[220:223], v155 offset:7168
	s_waitcnt vmcnt(8) lgkmcnt(0)
	s_setprio 1
	s_barrier
	v_mfma_f32_16x16x32_bf16 v[126:129], v[146:149], v[184:187], v[126:129]
	v_mfma_f32_16x16x32_bf16 v[118:121], v[160:163], v[184:187], v[118:121]
	v_mfma_f32_16x16x32_bf16 v[110:113], v[146:149], v[192:195], v[110:113]
	v_mfma_f32_16x16x32_bf16 v[102:105], v[160:163], v[192:195], v[102:105]
	v_mfma_f32_16x16x32_bf16 v[94:97], v[146:149], v[208:211], v[94:97]
	v_mfma_f32_16x16x32_bf16 v[86:89], v[160:163], v[208:211], v[86:89]
	v_mfma_f32_16x16x32_bf16 v[78:81], v[146:149], v[216:219], v[78:81]
	v_mfma_f32_16x16x32_bf16 v[70:73], v[160:163], v[216:219], v[70:73]
	v_mfma_f32_16x16x32_bf16 v[126:129], v[156:159], v[188:191], v[126:129]
	v_mfma_f32_16x16x32_bf16 v[118:121], v[164:167], v[188:191], v[118:121]
	v_mfma_f32_16x16x32_bf16 v[110:113], v[156:159], v[204:207], v[110:113]
	v_mfma_f32_16x16x32_bf16 v[102:105], v[164:167], v[204:207], v[102:105]
	v_mfma_f32_16x16x32_bf16 v[94:97], v[156:159], v[212:215], v[94:97]
	v_mfma_f32_16x16x32_bf16 v[86:89], v[164:167], v[212:215], v[86:89]
	v_mfma_f32_16x16x32_bf16 v[78:81], v[156:159], v[220:223], v[78:81]
	v_mfma_f32_16x16x32_bf16 v[70:73], v[164:167], v[220:223], v[70:73]
	s_setprio 0
	s_setprio 1
	v_mfma_f32_16x16x32_bf16 v[122:125], v[168:171], v[184:187], v[122:125]
	v_mfma_f32_16x16x32_bf16 v[114:117], v[176:179], v[184:187], v[114:117]
	v_mfma_f32_16x16x32_bf16 v[106:109], v[168:171], v[192:195], v[106:109]
	v_mfma_f32_16x16x32_bf16 v[98:101], v[176:179], v[192:195], v[98:101]
	v_mfma_f32_16x16x32_bf16 v[90:93], v[168:171], v[208:211], v[90:93]
	v_mfma_f32_16x16x32_bf16 v[82:85], v[176:179], v[208:211], v[82:85]
	v_mfma_f32_16x16x32_bf16 v[74:77], v[168:171], v[216:219], v[74:77]
	v_mfma_f32_16x16x32_bf16 v[66:69], v[176:179], v[216:219], v[66:69]
	v_mfma_f32_16x16x32_bf16 v[122:125], v[172:175], v[188:191], v[122:125]
	v_mfma_f32_16x16x32_bf16 v[114:117], v[180:183], v[188:191], v[114:117]
	v_mfma_f32_16x16x32_bf16 v[106:109], v[172:175], v[204:207], v[106:109]
	v_mfma_f32_16x16x32_bf16 v[98:101], v[180:183], v[204:207], v[98:101]
	v_mfma_f32_16x16x32_bf16 v[90:93], v[172:175], v[212:215], v[90:93]
	v_mfma_f32_16x16x32_bf16 v[82:85], v[180:183], v[212:215], v[82:85]
	v_mfma_f32_16x16x32_bf16 v[74:77], v[172:175], v[220:223], v[74:77]
	v_mfma_f32_16x16x32_bf16 v[66:69], v[180:183], v[220:223], v[66:69]
	s_barrier
	s_setprio 0
	s_add_i32 s29, s29, s43
	s_mov_b32 m0, s29
	global_load_lds_dwordx4 v0, s[20:21]
	s_add_i32 m0, s29, 0x2000
	s_add_u32 s46, s20, 0x40000
	s_addc_u32 s47, s21, 0
	s_add_i32 s29, s30, s43
	global_load_lds_dwordx4 v130, s[20:21]
	s_mov_b32 m0, s29
	s_nop 0
	global_load_lds_dwordx4 v0, s[46:47]
	s_add_i32 m0, s29, 0x2000
	s_nop 0
	global_load_lds_dwordx4 v130, s[46:47]
	s_mov_b32 m0, s73
	s_nop 0
	global_load_lds_dwordx4 v134, s[56:57]
	s_mov_b32 m0, s74
	s_nop 0
	global_load_lds_dwordx4 v132, s[56:57]
	ds_read_b128 v[184:187], v155 offset:16384
	ds_read_b128 v[188:191], v155 offset:17408
	ds_read_b128 v[192:195], v155 offset:18432
	ds_read_b128 v[204:207], v155 offset:19456
	ds_read_b128 v[208:211], v155 offset:20480
	ds_read_b128 v[212:215], v155 offset:21504
	ds_read_b128 v[216:219], v155 offset:22528
	ds_read_b128 v[220:223], v155 offset:23552
	s_waitcnt vmcnt(8) lgkmcnt(0)
	s_setprio 1
	s_barrier
	v_mfma_f32_16x16x32_bf16 v[62:65], v[146:149], v[184:187], v[62:65]
	v_mfma_f32_16x16x32_bf16 v[54:57], v[160:163], v[184:187], v[54:57]
	v_mfma_f32_16x16x32_bf16 v[46:49], v[146:149], v[192:195], v[46:49]
	v_mfma_f32_16x16x32_bf16 v[38:41], v[160:163], v[192:195], v[38:41]
	v_mfma_f32_16x16x32_bf16 v[30:33], v[146:149], v[208:211], v[30:33]
	v_mfma_f32_16x16x32_bf16 v[22:25], v[160:163], v[208:211], v[22:25]
	v_mfma_f32_16x16x32_bf16 v[14:17], v[146:149], v[216:219], v[14:17]
	v_mfma_f32_16x16x32_bf16 v[6:9], v[160:163], v[216:219], v[6:9]
	v_mfma_f32_16x16x32_bf16 v[62:65], v[156:159], v[188:191], v[62:65]
	v_mfma_f32_16x16x32_bf16 v[54:57], v[164:167], v[188:191], v[54:57]
	v_mfma_f32_16x16x32_bf16 v[46:49], v[156:159], v[204:207], v[46:49]
	v_mfma_f32_16x16x32_bf16 v[38:41], v[164:167], v[204:207], v[38:41]
	v_mfma_f32_16x16x32_bf16 v[30:33], v[156:159], v[212:215], v[30:33]
	v_mfma_f32_16x16x32_bf16 v[22:25], v[164:167], v[212:215], v[22:25]
	v_mfma_f32_16x16x32_bf16 v[14:17], v[156:159], v[220:223], v[14:17]
	v_mfma_f32_16x16x32_bf16 v[6:9], v[164:167], v[220:223], v[6:9]
	s_setprio 0
	s_setprio 1
	v_mfma_f32_16x16x32_bf16 v[58:61], v[168:171], v[184:187], v[58:61]
	v_mfma_f32_16x16x32_bf16 v[50:53], v[176:179], v[184:187], v[50:53]
	v_mfma_f32_16x16x32_bf16 v[42:45], v[168:171], v[192:195], v[42:45]
	v_mfma_f32_16x16x32_bf16 v[34:37], v[176:179], v[192:195], v[34:37]
	v_mfma_f32_16x16x32_bf16 v[26:29], v[168:171], v[208:211], v[26:29]
	v_mfma_f32_16x16x32_bf16 v[18:21], v[176:179], v[208:211], v[18:21]
	v_mfma_f32_16x16x32_bf16 v[10:13], v[168:171], v[216:219], v[10:13]
	v_mfma_f32_16x16x32_bf16 v[2:5], v[176:179], v[216:219], v[2:5]
	v_mfma_f32_16x16x32_bf16 v[58:61], v[172:175], v[188:191], v[58:61]
	v_mfma_f32_16x16x32_bf16 v[50:53], v[180:183], v[188:191], v[50:53]
	v_mfma_f32_16x16x32_bf16 v[42:45], v[172:175], v[204:207], v[42:45]
	v_mfma_f32_16x16x32_bf16 v[34:37], v[180:183], v[204:207], v[34:37]
	v_mfma_f32_16x16x32_bf16 v[26:29], v[172:175], v[212:215], v[26:29]
	v_mfma_f32_16x16x32_bf16 v[18:21], v[180:183], v[212:215], v[18:21]
	v_mfma_f32_16x16x32_bf16 v[10:13], v[172:175], v[220:223], v[10:13]
	v_mfma_f32_16x16x32_bf16 v[2:5], v[180:183], v[220:223], v[2:5]
	s_barrier
; #define PG8_STAGE(bufoff, gbase, voff) do { _Pragma("unroll") for (int _i = 0; _i < 2; ++_i) \
;         __builtin_amdgcn_global_load_lds((const gunsigned*)((const gchar*)(gbase) + (voff)[_i]), (LAS unsigned*)(lds + (bufoff) + ldsw + _i * 8192), 16, 0, 0); } while (0)
; #define PG8_LDA(dst, b, h) do { _Pragma("unroll") for (int m = 0; m < 4; ++m) _Pragma("unroll") for (int k = 0; k < 2; ++k) dst[m][k] = *(const LAS bf16x8*)(lds + PG8_SA(b, h) + aoff + m * 2048 + k * 1024); } while (0)
; #define PG8_LDB(dst, b, h) do { _Pragma("unroll") for (int n = 0; n < 2; ++n) _Pragma("unroll") for (int k = 0; k < 2; ++k) dst[n][k] = *(const LAS bf16x8*)(lds + PG8_SB(b, h) + boff + n * 2048 + k * 1024); } while (0)
; #define PG8_MMA(ai, bj, At, Bt) do { __builtin_amdgcn_s_setprio(1); _Pragma("unroll") for (int m = 0; m < 4; ++m) _Pragma("unroll") for (int n = 0; n < 2; ++n) _Pragma("unroll") for (int k = 0; k < 2; ++k) \
;         acc[ai][bj][m][n] = __builtin_amdgcn_mfma_f32_16x16x32_bf16(Bt[n][k], At[m][k], acc[ai][bj][m][n], 0, 0, 0); __builtin_amdgcn_s_setprio(0); } while (0)
; #define PG8_WAIT_V(n) asm volatile("s_waitcnt vmcnt(" #n ")" ::: "memory")
; #define PG8_WAIT_L(n) asm volatile("s_waitcnt lgkmcnt(" #n ")" ::: "memory")
; #define PG8_BAR __builtin_amdgcn_s_barrier()
; #define PG8_SCHED __builtin_amdgcn_sched_barrier(0)
; template <class Epi, class Sched>
; __device__ __forceinline__ void gemm_phase(LAS unsigned char* lds, const int tid, const Gemm g, const Sched& S, const Epi& E) {
;     ...
;             PG8_LDB(B0, 1, 0); PG8_LDB(B1, 1, 1); PG8_SCHED; PG8_LDA(At, 1, 0); PG8_STAGE(PG8_SA(0, 1), a2 + hstep, voffA);
;             PG8_WAIT_V(8); PG8_WAIT_L(0); PG8_BAR; PG8_MMA(0, 0, At, B0); PG8_MMA(0, 1, At, B1); PG8_BAR; PG8_SCHED;
;             PG8_LDA(At, 1, 1); PG8_STAGE(PG8_SB(1, 0), b3, voffB); PG8_STAGE(PG8_SB(1, 1), b3 + hstep, voffB); PG8_STAGE(PG8_SA(1, 0), a3, voffA);
;             PG8_WAIT_V(8); PG8_WAIT_L(0); PG8_BAR; PG8_MMA(1, 0, At, B0); PG8_MMA(1, 1, At, B1); PG8_BAR; PG8_SCHED;
;         }
;         if (wr == 0) PG8_BAR;
	s_setprio 0
	s_add_i32 s29, 0, 0x18000
	v_add_u32_e32 v142, s29, v145
	s_add_i32 s30, 0, 0x1c000
	s_add_u32 s46, s56, 0x40000
	s_addc_u32 s47, s57, 0
	s_mov_b32 m0, s75
	global_load_lds_dwordx4 v134, s[46:47]
	s_mov_b32 m0, s92
	s_nop 0
	global_load_lds_dwordx4 v132, s[46:47]
	ds_read_b128 v[146:149], v142
	ds_read_b128 v[156:159], v142 offset:1024
	ds_read_b128 v[160:163], v142 offset:2048
	ds_read_b128 v[164:167], v142 offset:3072
	v_add_u32_e32 v142, s30, v145
	ds_read_b128 v[168:171], v142
	ds_read_b128 v[172:175], v142 offset:1024
	ds_read_b128 v[176:179], v142 offset:2048
	ds_read_b128 v[180:183], v142 offset:3072
	ds_read_b128 v[184:187], v155 offset:32768
	ds_read_b128 v[188:191], v155 offset:33792
	ds_read_b128 v[192:195], v155 offset:34816
	ds_read_b128 v[204:207], v155 offset:35840
	ds_read_b128 v[208:211], v155 offset:36864
	ds_read_b128 v[212:215], v155 offset:37888
	ds_read_b128 v[216:219], v155 offset:38912
	ds_read_b128 v[220:223], v155 offset:39936
	s_waitcnt vmcnt(8) lgkmcnt(0)
	s_setprio 1
	s_barrier
	v_mfma_f32_16x16x32_bf16 v[126:129], v[146:149], v[184:187], v[126:129]
	v_mfma_f32_16x16x32_bf16 v[118:121], v[160:163], v[184:187], v[118:121]
	v_mfma_f32_16x16x32_bf16 v[110:113], v[146:149], v[192:195], v[110:113]
	v_mfma_f32_16x16x32_bf16 v[102:105], v[160:163], v[192:195], v[102:105]
	v_mfma_f32_16x16x32_bf16 v[94:97], v[146:149], v[208:211], v[94:97]
	v_mfma_f32_16x16x32_bf16 v[86:89], v[160:163], v[208:211], v[86:89]
	v_mfma_f32_16x16x32_bf16 v[78:81], v[146:149], v[216:219], v[78:81]
	v_mfma_f32_16x16x32_bf16 v[70:73], v[160:163], v[216:219], v[70:73]
	v_mfma_f32_16x16x32_bf16 v[126:129], v[156:159], v[188:191], v[126:129]
	v_mfma_f32_16x16x32_bf16 v[118:121], v[164:167], v[188:191], v[118:121]
	v_mfma_f32_16x16x32_bf16 v[110:113], v[156:159], v[204:207], v[110:113]
	v_mfma_f32_16x16x32_bf16 v[102:105], v[164:167], v[204:207], v[102:105]
	v_mfma_f32_16x16x32_bf16 v[94:97], v[156:159], v[212:215], v[94:97]
	v_mfma_f32_16x16x32_bf16 v[86:89], v[164:167], v[212:215], v[86:89]
	v_mfma_f32_16x16x32_bf16 v[78:81], v[156:159], v[220:223], v[78:81]
	v_mfma_f32_16x16x32_bf16 v[70:73], v[164:167], v[220:223], v[70:73]
	s_setprio 0
	s_setprio 1
	v_mfma_f32_16x16x32_bf16 v[122:125], v[168:171], v[184:187], v[122:125]
	v_mfma_f32_16x16x32_bf16 v[114:117], v[176:179], v[184:187], v[114:117]
	v_mfma_f32_16x16x32_bf16 v[106:109], v[168:171], v[192:195], v[106:109]
	v_mfma_f32_16x16x32_bf16 v[98:101], v[176:179], v[192:195], v[98:101]
	v_mfma_f32_16x16x32_bf16 v[90:93], v[168:171], v[208:211], v[90:93]
	v_mfma_f32_16x16x32_bf16 v[82:85], v[176:179], v[208:211], v[82:85]
	v_mfma_f32_16x16x32_bf16 v[74:77], v[168:171], v[216:219], v[74:77]
	v_mfma_f32_16x16x32_bf16 v[66:69], v[176:179], v[216:219], v[66:69]
	v_mfma_f32_16x16x32_bf16 v[122:125], v[172:175], v[188:191], v[122:125]
	v_mfma_f32_16x16x32_bf16 v[114:117], v[180:183], v[188:191], v[114:117]
	v_mfma_f32_16x16x32_bf16 v[106:109], v[172:175], v[204:207], v[106:109]
	v_mfma_f32_16x16x32_bf16 v[98:101], v[180:183], v[204:207], v[98:101]
	v_mfma_f32_16x16x32_bf16 v[90:93], v[172:175], v[212:215], v[90:93]
	v_mfma_f32_16x16x32_bf16 v[82:85], v[180:183], v[212:215], v[82:85]
	v_mfma_f32_16x16x32_bf16 v[74:77], v[172:175], v[220:223], v[74:77]
	v_mfma_f32_16x16x32_bf16 v[66:69], v[180:183], v[220:223], v[66:69]
	s_barrier
	s_setprio 0
	s_add_i32 s29, s29, s43
	s_mov_b32 m0, s29
	ds_read_b128 v[184:187], v155 offset:49152
	global_load_lds_dwordx4 v141, s[20:21]
	s_add_i32 m0, s29, 0x2000
	s_add_i32 s29, s30, s43
	global_load_lds_dwordx4 v153, s[20:21]
	s_add_u32 s20, s20, 0x40080
	s_addc_u32 s21, s21, 0
	s_mov_b32 m0, s29
	s_nop 0
	global_load_lds_dwordx4 v0, s[20:21]
	s_add_i32 m0, s29, 0x2000
	s_nop 0
	global_load_lds_dwordx4 v130, s[20:21]
	s_mov_b32 m0, s93
	s_nop 0
	global_load_lds_dwordx4 v201, s[56:57]
	s_mov_b32 m0, s44
	s_nop 0
	global_load_lds_dwordx4 v225, s[56:57]
	ds_read_b128 v[188:191], v155 offset:50176
	ds_read_b128 v[192:195], v155 offset:51200
	ds_read_b128 v[204:207], v155 offset:52224
	ds_read_b128 v[208:211], v155 offset:53248
	ds_read_b128 v[212:215], v155 offset:54272
	ds_read_b128 v[216:219], v155 offset:55296
	ds_read_b128 v[220:223], v155 offset:56320
	s_waitcnt vmcnt(8) lgkmcnt(0)
	s_setprio 1
	s_barrier
	v_mfma_f32_16x16x32_bf16 v[62:65], v[146:149], v[184:187], v[62:65]
	v_mfma_f32_16x16x32_bf16 v[54:57], v[160:163], v[184:187], v[54:57]
	v_mfma_f32_16x16x32_bf16 v[46:49], v[146:149], v[192:195], v[46:49]
	v_mfma_f32_16x16x32_bf16 v[38:41], v[160:163], v[192:195], v[38:41]
	v_mfma_f32_16x16x32_bf16 v[30:33], v[146:149], v[208:211], v[30:33]
	v_mfma_f32_16x16x32_bf16 v[22:25], v[160:163], v[208:211], v[22:25]
	v_mfma_f32_16x16x32_bf16 v[14:17], v[146:149], v[216:219], v[14:17]
	v_mfma_f32_16x16x32_bf16 v[6:9], v[160:163], v[216:219], v[6:9]
	v_mfma_f32_16x16x32_bf16 v[62:65], v[156:159], v[188:191], v[62:65]
	v_mfma_f32_16x16x32_bf16 v[54:57], v[164:167], v[188:191], v[54:57]
	v_mfma_f32_16x16x32_bf16 v[46:49], v[156:159], v[204:207], v[46:49]
	v_mfma_f32_16x16x32_bf16 v[38:41], v[164:167], v[204:207], v[38:41]
	v_mfma_f32_16x16x32_bf16 v[30:33], v[156:159], v[212:215], v[30:33]
	v_mfma_f32_16x16x32_bf16 v[22:25], v[164:167], v[212:215], v[22:25]
	v_mfma_f32_16x16x32_bf16 v[14:17], v[156:159], v[220:223], v[14:17]
	v_mfma_f32_16x16x32_bf16 v[6:9], v[164:167], v[220:223], v[6:9]
	s_setprio 0
	s_setprio 1
	v_mfma_f32_16x16x32_bf16 v[58:61], v[168:171], v[184:187], v[58:61]
	v_mfma_f32_16x16x32_bf16 v[50:53], v[176:179], v[184:187], v[50:53]
	v_mfma_f32_16x16x32_bf16 v[42:45], v[168:171], v[192:195], v[42:45]
	v_mfma_f32_16x16x32_bf16 v[34:37], v[176:179], v[192:195], v[34:37]
	v_mfma_f32_16x16x32_bf16 v[26:29], v[168:171], v[208:211], v[26:29]
	v_mfma_f32_16x16x32_bf16 v[18:21], v[176:179], v[208:211], v[18:21]
	v_mfma_f32_16x16x32_bf16 v[10:13], v[168:171], v[216:219], v[10:13]
	v_mfma_f32_16x16x32_bf16 v[2:5], v[176:179], v[216:219], v[2:5]
	v_mfma_f32_16x16x32_bf16 v[58:61], v[172:175], v[188:191], v[58:61]
	v_mfma_f32_16x16x32_bf16 v[50:53], v[180:183], v[188:191], v[50:53]
	v_mfma_f32_16x16x32_bf16 v[42:45], v[172:175], v[204:207], v[42:45]
	v_mfma_f32_16x16x32_bf16 v[34:37], v[180:183], v[204:207], v[34:37]
	v_mfma_f32_16x16x32_bf16 v[26:29], v[172:175], v[212:215], v[26:29]
	v_mfma_f32_16x16x32_bf16 v[18:21], v[180:183], v[212:215], v[18:21]
	v_mfma_f32_16x16x32_bf16 v[10:13], v[172:175], v[220:223], v[10:13]
	v_mfma_f32_16x16x32_bf16 v[2:5], v[180:183], v[220:223], v[2:5]
	s_barrier
	s_setprio 0
	s_add_i32 s31, s31, 2
	s_add_u32 s23, s23, 0x100
	s_addc_u32 s24, s24, 0
	s_add_u32 s16, s16, 0x100
	s_addc_u32 s17, s17, 0
	s_cmp_gt_u32 s31, 13
	s_cbranch_scc0 .LBB0_369
	s_and_b64 vcc, exec, s[6:7]
	s_cbranch_vccz .LBB0_372
	s_barrier

; #define PG8_STAGE(bufoff, gbase, voff) do { _Pragma("unroll") for (int _i = 0; _i < 2; ++_i) \
;         __builtin_amdgcn_global_load_lds((const gunsigned*)((const gchar*)(gbase) + (voff)[_i]), (LAS unsigned*)(lds + (bufoff) + ldsw + _i * 8192), 16, 0, 0); } while (0)
; #define PG8_LDA(dst, b, h) do { _Pragma("unroll") for (int m = 0; m < 4; ++m) _Pragma("unroll") for (int k = 0; k < 2; ++k) dst[m][k] = *(const LAS bf16x8*)(lds + PG8_SA(b, h) + aoff + m * 2048 + k * 1024); } while (0)
; #define PG8_LDB(dst, b, h) do { _Pragma("unroll") for (int n = 0; n < 2; ++n) _Pragma("unroll") for (int k = 0; k < 2; ++k) dst[n][k] = *(const LAS bf16x8*)(lds + PG8_SB(b, h) + boff + n * 2048 + k * 1024); } while (0)
; #define PG8_MMA(ai, bj, At, Bt) do { __builtin_amdgcn_s_setprio(1); _Pragma("unroll") for (int m = 0; m < 4; ++m) _Pragma("unroll") for (int n = 0; n < 2; ++n) _Pragma("unroll") for (int k = 0; k < 2; ++k) \
;         acc[ai][bj][m][n] = __builtin_amdgcn_mfma_f32_16x16x32_bf16(Bt[n][k], At[m][k], acc[ai][bj][m][n], 0, 0, 0); __builtin_amdgcn_s_setprio(0); } while (0)
; #define PG8_WAIT_V(n) asm volatile("s_waitcnt vmcnt(" #n ")" ::: "memory")
; #define PG8_WAIT_L(n) asm volatile("s_waitcnt lgkmcnt(" #n ")" ::: "memory")
; #define PG8_BAR __builtin_amdgcn_s_barrier()
; #define PG8_SCHED __builtin_amdgcn_sched_barrier(0)
; template <class Epi, class Sched>
; __device__ __forceinline__ void gemm_phase(LAS unsigned char* lds, const int tid, const Gemm g, const Sched& S, const Epi& E) {
;     ...
;         for (int t = 0; t < nt; t += 2) {
;             const bool last = (t == nt - 2);
;             const gchar* a1 = cA + (size_t)(t + 1) * kstep;
;             const gchar* a2 = last ? nA : cA + (size_t)(t + 2) * kstep; const gchar* b2 = last ? nB : cB + (size_t)(t + 2) * kstep;
;             const gchar* a3 = a2 + kstep; const gchar* b3 = b2 + kstep;
;             PG8_LDB(B0, 0, 0); PG8_LDB(B1, 0, 1); PG8_SCHED; PG8_LDA(At, 0, 0); PG8_STAGE(PG8_SA(1, 1), a1 + hstep, voffA);
;             PG8_WAIT_V(8); PG8_WAIT_L(0); PG8_BAR; PG8_MMA(0, 0, At, B0); PG8_MMA(0, 1, At, B1); PG8_BAR; PG8_SCHED;
;             PG8_LDA(At, 0, 1); PG8_STAGE(PG8_SB(0, 0), b2, voffB); PG8_STAGE(PG8_SB(0, 1), b2 + hstep, voffB); PG8_STAGE(PG8_SA(0, 0), a2, voffA);
;             PG8_WAIT_V(8); PG8_WAIT_L(0); PG8_BAR; PG8_MMA(1, 0, At, B0); PG8_MMA(1, 1, At, B1); PG8_BAR; PG8_SCHED;
.LBB0_397:
	s_add_u32 s20, s92, 0xfffc0080
	s_addc_u32 s21, s93, -1
	s_add_i32 s29, 0, 0x10000
	s_cmp_eq_u32 s53, 12
	s_cselect_b32 s73, s1, s21
	s_cselect_b32 s72, s31, s20
	s_cselect_b32 s21, s17, s52
	s_cselect_b32 s20, s50, s51
	s_add_i32 s30, 0, 0x14000
	s_add_i32 m0, s43, 0xc000
	global_load_lds_dwordx4 v162, s[92:93]
	s_add_i32 m0, s43, 0xe000
	s_nop 0
	global_load_lds_dwordx4 v160, s[92:93]
	v_add_u32_e32 v142, s29, v177
	v_add_u32_e32 v168, s30, v177
	ds_read_b128 v[130:133], v142
	ds_read_b128 v[134:137], v142 offset:1024
	ds_read_b128 v[138:141], v142 offset:2048
	ds_read_b128 v[142:145], v142 offset:3072
	ds_read_b128 v[146:149], v168
	ds_read_b128 v[150:153], v168 offset:1024
	ds_read_b128 v[164:167], v168 offset:2048
	ds_read_b128 v[168:171], v168 offset:3072
	ds_read_b128 v[172:175], v181
	ds_read_b128 v[182:185], v181 offset:1024
	ds_read_b128 v[186:189], v181 offset:2048
	ds_read_b128 v[190:193], v181 offset:3072
	ds_read_b128 v[204:207], v181 offset:4096
	ds_read_b128 v[208:211], v181 offset:5120
	ds_read_b128 v[212:215], v181 offset:6144
	ds_read_b128 v[216:219], v181 offset:7168
	s_waitcnt vmcnt(8) lgkmcnt(0)
	s_setprio 1
	s_barrier
	v_mfma_f32_16x16x32_bf16 v[126:129], v[130:133], v[172:175], v[126:129]
	v_mfma_f32_16x16x32_bf16 v[122:125], v[138:141], v[172:175], v[122:125]
	v_mfma_f32_16x16x32_bf16 v[110:113], v[130:133], v[186:189], v[110:113]
	v_mfma_f32_16x16x32_bf16 v[106:109], v[138:141], v[186:189], v[106:109]
	v_mfma_f32_16x16x32_bf16 v[94:97], v[130:133], v[204:207], v[94:97]
	v_mfma_f32_16x16x32_bf16 v[90:93], v[138:141], v[204:207], v[90:93]
	v_mfma_f32_16x16x32_bf16 v[78:81], v[130:133], v[212:215], v[78:81]
	v_mfma_f32_16x16x32_bf16 v[74:77], v[138:141], v[212:215], v[74:77]
	v_mfma_f32_16x16x32_bf16 v[126:129], v[134:137], v[182:185], v[126:129]
	v_mfma_f32_16x16x32_bf16 v[122:125], v[142:145], v[182:185], v[122:125]
	v_mfma_f32_16x16x32_bf16 v[110:113], v[134:137], v[190:193], v[110:113]
	v_mfma_f32_16x16x32_bf16 v[106:109], v[142:145], v[190:193], v[106:109]
	v_mfma_f32_16x16x32_bf16 v[94:97], v[134:137], v[208:211], v[94:97]
	v_mfma_f32_16x16x32_bf16 v[90:93], v[142:145], v[208:211], v[90:93]
	v_mfma_f32_16x16x32_bf16 v[78:81], v[134:137], v[216:219], v[78:81]
	v_mfma_f32_16x16x32_bf16 v[74:77], v[142:145], v[216:219], v[74:77]
	s_setprio 0
	s_setprio 1
	v_mfma_f32_16x16x32_bf16 v[118:121], v[146:149], v[172:175], v[118:121]
	v_mfma_f32_16x16x32_bf16 v[114:117], v[164:167], v[172:175], v[114:117]
	v_mfma_f32_16x16x32_bf16 v[102:105], v[146:149], v[186:189], v[102:105]
	v_mfma_f32_16x16x32_bf16 v[98:101], v[164:167], v[186:189], v[98:101]
	v_mfma_f32_16x16x32_bf16 v[86:89], v[146:149], v[204:207], v[86:89]
	v_mfma_f32_16x16x32_bf16 v[82:85], v[164:167], v[204:207], v[82:85]
	v_mfma_f32_16x16x32_bf16 v[70:73], v[146:149], v[212:215], v[70:73]
	v_mfma_f32_16x16x32_bf16 v[66:69], v[164:167], v[212:215], v[66:69]
	v_mfma_f32_16x16x32_bf16 v[118:121], v[150:153], v[182:185], v[118:121]
	v_mfma_f32_16x16x32_bf16 v[114:117], v[168:171], v[182:185], v[114:117]
	v_mfma_f32_16x16x32_bf16 v[102:105], v[150:153], v[190:193], v[102:105]
	v_mfma_f32_16x16x32_bf16 v[98:101], v[168:171], v[190:193], v[98:101]
	v_mfma_f32_16x16x32_bf16 v[86:89], v[150:153], v[208:211], v[86:89]
	v_mfma_f32_16x16x32_bf16 v[82:85], v[168:171], v[208:211], v[82:85]
	v_mfma_f32_16x16x32_bf16 v[70:73], v[150:153], v[216:219], v[70:73]
	v_mfma_f32_16x16x32_bf16 v[66:69], v[168:171], v[216:219], v[66:69]
	s_barrier
	s_setprio 0
	s_add_i32 s29, s29, s15
	s_mov_b32 m0, s29
	global_load_lds_dwordx4 v0, s[20:21]
	s_add_i32 m0, s29, 0x2000
	s_add_u32 s54, s20, 0x40000
	s_addc_u32 s55, s21, 0
	s_add_i32 s29, s30, s15
	global_load_lds_dwordx4 v158, s[20:21]
	s_mov_b32 m0, s29
	s_nop 0
	global_load_lds_dwordx4 v0, s[54:55]
	s_add_i32 m0, s29, 0x2000
	s_nop 0
	global_load_lds_dwordx4 v158, s[54:55]
	s_mov_b32 m0, s43
	s_nop 0
	global_load_lds_dwordx4 v154, s[72:73]
	s_mov_b32 m0, s44
	s_nop 0
	global_load_lds_dwordx4 v156, s[72:73]
	ds_read_b128 v[172:175], v181 offset:16384
	ds_read_b128 v[182:185], v181 offset:17408
	ds_read_b128 v[186:189], v181 offset:18432
	ds_read_b128 v[190:193], v181 offset:19456
	ds_read_b128 v[204:207], v181 offset:20480
	ds_read_b128 v[208:211], v181 offset:21504
	ds_read_b128 v[212:215], v181 offset:22528
	ds_read_b128 v[216:219], v181 offset:23552
	s_waitcnt vmcnt(8) lgkmcnt(0)
	s_setprio 1
	s_barrier
	v_mfma_f32_16x16x32_bf16 v[62:65], v[130:133], v[172:175], v[62:65]
	v_mfma_f32_16x16x32_bf16 v[58:61], v[138:141], v[172:175], v[58:61]
	v_mfma_f32_16x16x32_bf16 v[46:49], v[130:133], v[186:189], v[46:49]
	v_mfma_f32_16x16x32_bf16 v[42:45], v[138:141], v[186:189], v[42:45]
	v_mfma_f32_16x16x32_bf16 v[30:33], v[130:133], v[204:207], v[30:33]
	v_mfma_f32_16x16x32_bf16 v[26:29], v[138:141], v[204:207], v[26:29]
	v_mfma_f32_16x16x32_bf16 v[14:17], v[130:133], v[212:215], v[14:17]
	v_mfma_f32_16x16x32_bf16 v[10:13], v[138:141], v[212:215], v[10:13]
	v_mfma_f32_16x16x32_bf16 v[62:65], v[134:137], v[182:185], v[62:65]
	v_mfma_f32_16x16x32_bf16 v[58:61], v[142:145], v[182:185], v[58:61]
	v_mfma_f32_16x16x32_bf16 v[46:49], v[134:137], v[190:193], v[46:49]
	v_mfma_f32_16x16x32_bf16 v[42:45], v[142:145], v[190:193], v[42:45]
	v_mfma_f32_16x16x32_bf16 v[30:33], v[134:137], v[208:211], v[30:33]
	v_mfma_f32_16x16x32_bf16 v[26:29], v[142:145], v[208:211], v[26:29]
	v_mfma_f32_16x16x32_bf16 v[14:17], v[134:137], v[216:219], v[14:17]
	v_mfma_f32_16x16x32_bf16 v[10:13], v[142:145], v[216:219], v[10:13]
	s_setprio 0
	s_setprio 1
	v_mfma_f32_16x16x32_bf16 v[54:57], v[146:149], v[172:175], v[54:57]
	v_mfma_f32_16x16x32_bf16 v[50:53], v[164:167], v[172:175], v[50:53]
	v_mfma_f32_16x16x32_bf16 v[38:41], v[146:149], v[186:189], v[38:41]
	v_mfma_f32_16x16x32_bf16 v[34:37], v[164:167], v[186:189], v[34:37]
	v_mfma_f32_16x16x32_bf16 v[22:25], v[146:149], v[204:207], v[22:25]
	v_mfma_f32_16x16x32_bf16 v[18:21], v[164:167], v[204:207], v[18:21]
	v_mfma_f32_16x16x32_bf16 v[6:9], v[146:149], v[212:215], v[6:9]
	v_mfma_f32_16x16x32_bf16 v[2:5], v[164:167], v[212:215], v[2:5]
	v_mfma_f32_16x16x32_bf16 v[54:57], v[150:153], v[182:185], v[54:57]
	v_mfma_f32_16x16x32_bf16 v[50:53], v[168:171], v[182:185], v[50:53]
	v_mfma_f32_16x16x32_bf16 v[38:41], v[150:153], v[190:193], v[38:41]
	v_mfma_f32_16x16x32_bf16 v[34:37], v[168:171], v[190:193], v[34:37]
	v_mfma_f32_16x16x32_bf16 v[22:25], v[150:153], v[208:211], v[22:25]
	v_mfma_f32_16x16x32_bf16 v[18:21], v[168:171], v[208:211], v[18:21]
	v_mfma_f32_16x16x32_bf16 v[6:9], v[150:153], v[216:219], v[6:9]
	v_mfma_f32_16x16x32_bf16 v[2:5], v[168:171], v[216:219], v[2:5]
	s_barrier
; #define PG8_STAGE(bufoff, gbase, voff) do { _Pragma("unroll") for (int _i = 0; _i < 2; ++_i) \
;         __builtin_amdgcn_global_load_lds((const gunsigned*)((const gchar*)(gbase) + (voff)[_i]), (LAS unsigned*)(lds + (bufoff) + ldsw + _i * 8192), 16, 0, 0); } while (0)
; #define PG8_LDA(dst, b, h) do { _Pragma("unroll") for (int m = 0; m < 4; ++m) _Pragma("unroll") for (int k = 0; k < 2; ++k) dst[m][k] = *(const LAS bf16x8*)(lds + PG8_SA(b, h) + aoff + m * 2048 + k * 1024); } while (0)
; #define PG8_LDB(dst, b, h) do { _Pragma("unroll") for (int n = 0; n < 2; ++n) _Pragma("unroll") for (int k = 0; k < 2; ++k) dst[n][k] = *(const LAS bf16x8*)(lds + PG8_SB(b, h) + boff + n * 2048 + k * 1024); } while (0)
; #define PG8_MMA(ai, bj, At, Bt) do { __builtin_amdgcn_s_setprio(1); _Pragma("unroll") for (int m = 0; m < 4; ++m) _Pragma("unroll") for (int n = 0; n < 2; ++n) _Pragma("unroll") for (int k = 0; k < 2; ++k) \
;         acc[ai][bj][m][n] = __builtin_amdgcn_mfma_f32_16x16x32_bf16(Bt[n][k], At[m][k], acc[ai][bj][m][n], 0, 0, 0); __builtin_amdgcn_s_setprio(0); } while (0)
; #define PG8_WAIT_V(n) asm volatile("s_waitcnt vmcnt(" #n ")" ::: "memory")
; #define PG8_WAIT_L(n) asm volatile("s_waitcnt lgkmcnt(" #n ")" ::: "memory")
; #define PG8_BAR __builtin_amdgcn_s_barrier()
; #define PG8_SCHED __builtin_amdgcn_sched_barrier(0)
; template <class Epi, class Sched>
; __device__ __forceinline__ void gemm_phase(LAS unsigned char* lds, const int tid, const Gemm g, const Sched& S, const Epi& E) {
;     ...
;             PG8_LDB(B0, 1, 0); PG8_LDB(B1, 1, 1); PG8_SCHED; PG8_LDA(At, 1, 0); PG8_STAGE(PG8_SA(0, 1), a2 + hstep, voffA);
;             PG8_WAIT_V(8); PG8_WAIT_L(0); PG8_BAR; PG8_MMA(0, 0, At, B0); PG8_MMA(0, 1, At, B1); PG8_BAR; PG8_SCHED;
;             PG8_LDA(At, 1, 1); PG8_STAGE(PG8_SB(1, 0), b3, voffB); PG8_STAGE(PG8_SB(1, 1), b3 + hstep, voffB); PG8_STAGE(PG8_SA(1, 0), a3, voffA);
;             PG8_WAIT_V(8); PG8_WAIT_L(0); PG8_BAR; PG8_MMA(1, 0, At, B0); PG8_MMA(1, 1, At, B1); PG8_BAR; PG8_SCHED;
;         }
;         if (wr == 0) PG8_BAR;
	s_setprio 0
	s_add_i32 s29, 0, 0x18000
	s_add_i32 s30, 0, 0x1c000
	s_add_u32 s54, s72, 0x40000
	s_addc_u32 s55, s73, 0
	s_mov_b32 m0, s45
	global_load_lds_dwordx4 v154, s[54:55]
	s_mov_b32 m0, s46
	s_nop 0
	global_load_lds_dwordx4 v156, s[54:55]
	v_add_u32_e32 v142, s29, v177
	v_add_u32_e32 v168, s30, v177
	ds_read_b128 v[130:133], v142
	ds_read_b128 v[134:137], v142 offset:1024
	ds_read_b128 v[138:141], v142 offset:2048
	ds_read_b128 v[142:145], v142 offset:3072
	ds_read_b128 v[146:149], v168
	ds_read_b128 v[150:153], v168 offset:1024
	ds_read_b128 v[164:167], v168 offset:2048
	ds_read_b128 v[168:171], v168 offset:3072
	ds_read_b128 v[172:175], v181 offset:32768
	ds_read_b128 v[182:185], v181 offset:33792
	ds_read_b128 v[186:189], v181 offset:34816
	ds_read_b128 v[190:193], v181 offset:35840
	ds_read_b128 v[204:207], v181 offset:36864
	ds_read_b128 v[208:211], v181 offset:37888
	ds_read_b128 v[212:215], v181 offset:38912
	ds_read_b128 v[216:219], v181 offset:39936
	s_waitcnt vmcnt(8) lgkmcnt(0)
	s_setprio 1
	s_barrier
	v_mfma_f32_16x16x32_bf16 v[126:129], v[130:133], v[172:175], v[126:129]
	v_mfma_f32_16x16x32_bf16 v[122:125], v[138:141], v[172:175], v[122:125]
	v_mfma_f32_16x16x32_bf16 v[110:113], v[130:133], v[186:189], v[110:113]
	v_mfma_f32_16x16x32_bf16 v[106:109], v[138:141], v[186:189], v[106:109]
	v_mfma_f32_16x16x32_bf16 v[94:97], v[130:133], v[204:207], v[94:97]
	v_mfma_f32_16x16x32_bf16 v[90:93], v[138:141], v[204:207], v[90:93]
	v_mfma_f32_16x16x32_bf16 v[78:81], v[130:133], v[212:215], v[78:81]
	v_mfma_f32_16x16x32_bf16 v[74:77], v[138:141], v[212:215], v[74:77]
	v_mfma_f32_16x16x32_bf16 v[126:129], v[134:137], v[182:185], v[126:129]
	v_mfma_f32_16x16x32_bf16 v[122:125], v[142:145], v[182:185], v[122:125]
	v_mfma_f32_16x16x32_bf16 v[110:113], v[134:137], v[190:193], v[110:113]
	v_mfma_f32_16x16x32_bf16 v[106:109], v[142:145], v[190:193], v[106:109]
	v_mfma_f32_16x16x32_bf16 v[94:97], v[134:137], v[208:211], v[94:97]
	v_mfma_f32_16x16x32_bf16 v[90:93], v[142:145], v[208:211], v[90:93]
	v_mfma_f32_16x16x32_bf16 v[78:81], v[134:137], v[216:219], v[78:81]
	v_mfma_f32_16x16x32_bf16 v[74:77], v[142:145], v[216:219], v[74:77]
	s_setprio 0
	s_setprio 1
	v_mfma_f32_16x16x32_bf16 v[118:121], v[146:149], v[172:175], v[118:121]
	v_mfma_f32_16x16x32_bf16 v[114:117], v[164:167], v[172:175], v[114:117]
	v_mfma_f32_16x16x32_bf16 v[102:105], v[146:149], v[186:189], v[102:105]
	v_mfma_f32_16x16x32_bf16 v[98:101], v[164:167], v[186:189], v[98:101]
	v_mfma_f32_16x16x32_bf16 v[86:89], v[146:149], v[204:207], v[86:89]
	v_mfma_f32_16x16x32_bf16 v[82:85], v[164:167], v[204:207], v[82:85]
	v_mfma_f32_16x16x32_bf16 v[70:73], v[146:149], v[212:215], v[70:73]
	v_mfma_f32_16x16x32_bf16 v[66:69], v[164:167], v[212:215], v[66:69]
	v_mfma_f32_16x16x32_bf16 v[118:121], v[150:153], v[182:185], v[118:121]
	v_mfma_f32_16x16x32_bf16 v[114:117], v[168:171], v[182:185], v[114:117]
	v_mfma_f32_16x16x32_bf16 v[102:105], v[150:153], v[190:193], v[102:105]
	v_mfma_f32_16x16x32_bf16 v[98:101], v[168:171], v[190:193], v[98:101]
	v_mfma_f32_16x16x32_bf16 v[86:89], v[150:153], v[208:211], v[86:89]
	v_mfma_f32_16x16x32_bf16 v[82:85], v[168:171], v[208:211], v[82:85]
	v_mfma_f32_16x16x32_bf16 v[70:73], v[150:153], v[216:219], v[70:73]
	v_mfma_f32_16x16x32_bf16 v[66:69], v[168:171], v[216:219], v[66:69]
	s_barrier
	s_setprio 0
	s_add_i32 s29, s29, s15
	s_mov_b32 m0, s29
	ds_read_b128 v[172:175], v181 offset:49152
	global_load_lds_dwordx4 v195, s[20:21]
	s_add_i32 m0, s29, 0x2000
	s_add_i32 s29, s30, s15
	global_load_lds_dwordx4 v201, s[20:21]
	s_add_u32 s20, s20, 0x40080
	s_addc_u32 s21, s21, 0
	s_mov_b32 m0, s29
	s_nop 0
	global_load_lds_dwordx4 v0, s[20:21]
	s_add_i32 m0, s29, 0x2000
	s_nop 0
	global_load_lds_dwordx4 v158, s[20:21]
	s_mov_b32 m0, s12
	s_nop 0
	global_load_lds_dwordx4 v221, s[72:73]
	s_mov_b32 m0, s47
	s_nop 0
	global_load_lds_dwordx4 v223, s[72:73]
	ds_read_b128 v[182:185], v181 offset:50176
	ds_read_b128 v[186:189], v181 offset:51200
	ds_read_b128 v[190:193], v181 offset:52224
	ds_read_b128 v[204:207], v181 offset:53248
	ds_read_b128 v[208:211], v181 offset:54272
	ds_read_b128 v[212:215], v181 offset:55296
	ds_read_b128 v[216:219], v181 offset:56320
	s_waitcnt vmcnt(8) lgkmcnt(0)
	s_setprio 1
	s_barrier
	v_mfma_f32_16x16x32_bf16 v[62:65], v[130:133], v[172:175], v[62:65]
	v_mfma_f32_16x16x32_bf16 v[58:61], v[138:141], v[172:175], v[58:61]
	v_mfma_f32_16x16x32_bf16 v[46:49], v[130:133], v[186:189], v[46:49]
	v_mfma_f32_16x16x32_bf16 v[42:45], v[138:141], v[186:189], v[42:45]
	v_mfma_f32_16x16x32_bf16 v[30:33], v[130:133], v[204:207], v[30:33]
	v_mfma_f32_16x16x32_bf16 v[26:29], v[138:141], v[204:207], v[26:29]
	v_mfma_f32_16x16x32_bf16 v[14:17], v[130:133], v[212:215], v[14:17]
	v_mfma_f32_16x16x32_bf16 v[10:13], v[138:141], v[212:215], v[10:13]
	v_mfma_f32_16x16x32_bf16 v[62:65], v[134:137], v[182:185], v[62:65]
	v_mfma_f32_16x16x32_bf16 v[58:61], v[142:145], v[182:185], v[58:61]
	v_mfma_f32_16x16x32_bf16 v[46:49], v[134:137], v[190:193], v[46:49]
	v_mfma_f32_16x16x32_bf16 v[42:45], v[142:145], v[190:193], v[42:45]
	v_mfma_f32_16x16x32_bf16 v[30:33], v[134:137], v[208:211], v[30:33]
	v_mfma_f32_16x16x32_bf16 v[26:29], v[142:145], v[208:211], v[26:29]
	v_mfma_f32_16x16x32_bf16 v[14:17], v[134:137], v[216:219], v[14:17]
	v_mfma_f32_16x16x32_bf16 v[10:13], v[142:145], v[216:219], v[10:13]
	s_setprio 0
	s_setprio 1
	v_mfma_f32_16x16x32_bf16 v[54:57], v[146:149], v[172:175], v[54:57]
	v_mfma_f32_16x16x32_bf16 v[50:53], v[164:167], v[172:175], v[50:53]
	v_mfma_f32_16x16x32_bf16 v[38:41], v[146:149], v[186:189], v[38:41]
	v_mfma_f32_16x16x32_bf16 v[34:37], v[164:167], v[186:189], v[34:37]
	v_mfma_f32_16x16x32_bf16 v[22:25], v[146:149], v[204:207], v[22:25]
	v_mfma_f32_16x16x32_bf16 v[18:21], v[164:167], v[204:207], v[18:21]
	v_mfma_f32_16x16x32_bf16 v[6:9], v[146:149], v[212:215], v[6:9]
	v_mfma_f32_16x16x32_bf16 v[2:5], v[164:167], v[212:215], v[2:5]
	v_mfma_f32_16x16x32_bf16 v[54:57], v[150:153], v[182:185], v[54:57]
	v_mfma_f32_16x16x32_bf16 v[50:53], v[168:171], v[182:185], v[50:53]
	v_mfma_f32_16x16x32_bf16 v[38:41], v[150:153], v[190:193], v[38:41]
	v_mfma_f32_16x16x32_bf16 v[34:37], v[168:171], v[190:193], v[34:37]
	v_mfma_f32_16x16x32_bf16 v[22:25], v[150:153], v[208:211], v[22:25]
	v_mfma_f32_16x16x32_bf16 v[18:21], v[168:171], v[208:211], v[18:21]
	v_mfma_f32_16x16x32_bf16 v[6:9], v[150:153], v[216:219], v[6:9]
	v_mfma_f32_16x16x32_bf16 v[2:5], v[168:171], v[216:219], v[2:5]
	s_barrier
	s_setprio 0
	s_add_i32 s53, s53, 2
	s_add_u32 s51, s51, 0x100
	s_addc_u32 s52, s52, 0
	s_add_u32 s92, s92, 0x100
	s_addc_u32 s93, s93, 0
	s_cmp_gt_u32 s53, 13
	s_cbranch_scc0 .LBB0_397
	s_and_b64 vcc, exec, s[10:11]
	s_cbranch_vccz .LBB0_400
	s_barrier

; #define PG8_STAGE(bufoff, gbase, voff) do { _Pragma("unroll") for (int _i = 0; _i < 2; ++_i) \
;         __builtin_amdgcn_global_load_lds((const gunsigned*)((const gchar*)(gbase) + (voff)[_i]), (LAS unsigned*)(lds + (bufoff) + ldsw + _i * 8192), 16, 0, 0); } while (0)
; #define PG8_LDA(dst, b, h) do { _Pragma("unroll") for (int m = 0; m < 4; ++m) _Pragma("unroll") for (int k = 0; k < 2; ++k) dst[m][k] = *(const LAS bf16x8*)(lds + PG8_SA(b, h) + aoff + m * 2048 + k * 1024); } while (0)
; #define PG8_LDB(dst, b, h) do { _Pragma("unroll") for (int n = 0; n < 2; ++n) _Pragma("unroll") for (int k = 0; k < 2; ++k) dst[n][k] = *(const LAS bf16x8*)(lds + PG8_SB(b, h) + boff + n * 2048 + k * 1024); } while (0)
; #define PG8_MMA(ai, bj, At, Bt) do { __builtin_amdgcn_s_setprio(1); _Pragma("unroll") for (int m = 0; m < 4; ++m) _Pragma("unroll") for (int n = 0; n < 2; ++n) _Pragma("unroll") for (int k = 0; k < 2; ++k) \
;         acc[ai][bj][m][n] = __builtin_amdgcn_mfma_f32_16x16x32_bf16(Bt[n][k], At[m][k], acc[ai][bj][m][n], 0, 0, 0); __builtin_amdgcn_s_setprio(0); } while (0)
; #define PG8_WAIT_V(n) asm volatile("s_waitcnt vmcnt(" #n ")" ::: "memory")
; #define PG8_WAIT_L(n) asm volatile("s_waitcnt lgkmcnt(" #n ")" ::: "memory")
; #define PG8_BAR __builtin_amdgcn_s_barrier()
; #define PG8_SCHED __builtin_amdgcn_sched_barrier(0)
; template <class Epi, class Sched>
; __device__ __forceinline__ void gemm_phase(LAS unsigned char* lds, const int tid, const Gemm g, const Sched& S, const Epi& E) {
;     ...
;         for (int t = 0; t < nt; t += 2) {
;             const bool last = (t == nt - 2);
;             const gchar* a1 = cA + (size_t)(t + 1) * kstep;
;             const gchar* a2 = last ? nA : cA + (size_t)(t + 2) * kstep; const gchar* b2 = last ? nB : cB + (size_t)(t + 2) * kstep;
;             const gchar* a3 = a2 + kstep; const gchar* b3 = b2 + kstep;
;             PG8_LDB(B0, 0, 0); PG8_LDB(B1, 0, 1); PG8_SCHED; PG8_LDA(At, 0, 0); PG8_STAGE(PG8_SA(1, 1), a1 + hstep, voffA);
;             PG8_WAIT_V(8); PG8_WAIT_L(0); PG8_BAR; PG8_MMA(0, 0, At, B0); PG8_MMA(0, 1, At, B1); PG8_BAR; PG8_SCHED;
;             PG8_LDA(At, 0, 1); PG8_STAGE(PG8_SB(0, 0), b2, voffB); PG8_STAGE(PG8_SB(0, 1), b2 + hstep, voffB); PG8_STAGE(PG8_SA(0, 0), a2, voffA);
;             PG8_WAIT_V(8); PG8_WAIT_L(0); PG8_BAR; PG8_MMA(1, 0, At, B0); PG8_MMA(1, 1, At, B1); PG8_BAR; PG8_SCHED;
.LBB0_444:
	s_add_u32 s20, s16, 0xfffe0080
	s_addc_u32 s21, s17, -1
	s_add_i32 s29, 0, 0x10000
	s_cmp_eq_u32 s51, 4
	s_cselect_b32 s73, s1, s21
	s_cselect_b32 s72, s5, s20
	s_cselect_b32 s21, s15, s31
	s_cselect_b32 s20, s23, s24
	s_add_i32 s30, 0, 0x14000
	s_add_i32 m0, s93, 0xc000
	global_load_lds_dwordx4 v212, s[16:17]
	s_add_i32 m0, s93, 0xe000
	s_nop 0
	global_load_lds_dwordx4 v210, s[16:17]
	v_add_u32_e32 v122, s29, v242
	ds_read_b128 v[132:135], v122
	ds_read_b128 v[136:139], v122 offset:1024
	ds_read_b128 v[140:143], v122 offset:2048
	ds_read_b128 v[144:147], v122 offset:3072
	v_add_u32_e32 v122, s30, v242
	ds_read_b128 v[148:151], v122
	ds_read_b128 v[152:155], v122 offset:1024
	ds_read_b128 v[156:159], v122 offset:2048
	ds_read_b128 v[160:163], v122 offset:3072
	ds_read_b128 v[164:167], v244
	ds_read_b128 v[168:171], v244 offset:1024
	ds_read_b128 v[172:175], v244 offset:2048
	ds_read_b128 v[176:179], v244 offset:3072
	ds_read_b128 v[180:183], v244 offset:4096
	ds_read_b128 v[184:187], v244 offset:5120
	ds_read_b128 v[188:191], v244 offset:6144
	ds_read_b128 v[192:195], v244 offset:7168
	s_waitcnt vmcnt(8) lgkmcnt(0)
	s_setprio 1
	s_barrier
	v_mfma_f32_16x16x32_bf16 v[128:131], v[132:135], v[164:167], v[128:131]
	v_mfma_f32_16x16x32_bf16 v[122:125], v[140:143], v[164:167], v[124:127]
	v_mfma_f32_16x16x32_bf16 v[110:113], v[132:135], v[172:175], v[110:113]
	v_mfma_f32_16x16x32_bf16 v[106:109], v[140:143], v[172:175], v[106:109]
	v_mfma_f32_16x16x32_bf16 v[94:97], v[132:135], v[180:183], v[94:97]
	v_mfma_f32_16x16x32_bf16 v[90:93], v[140:143], v[180:183], v[90:93]
	v_mfma_f32_16x16x32_bf16 v[78:81], v[132:135], v[188:191], v[78:81]
	v_mfma_f32_16x16x32_bf16 v[74:77], v[140:143], v[188:191], v[74:77]
	v_mfma_f32_16x16x32_bf16 v[128:131], v[136:139], v[168:171], v[128:131]
	v_mfma_f32_16x16x32_bf16 v[122:125], v[144:147], v[168:171], v[122:125]
	v_mfma_f32_16x16x32_bf16 v[110:113], v[136:139], v[176:179], v[110:113]
	v_mfma_f32_16x16x32_bf16 v[106:109], v[144:147], v[176:179], v[106:109]
	v_mfma_f32_16x16x32_bf16 v[94:97], v[136:139], v[184:187], v[94:97]
	v_mfma_f32_16x16x32_bf16 v[90:93], v[144:147], v[184:187], v[90:93]
	v_mfma_f32_16x16x32_bf16 v[78:81], v[136:139], v[192:195], v[78:81]
	v_mfma_f32_16x16x32_bf16 v[74:77], v[144:147], v[192:195], v[74:77]
	s_setprio 0
	s_setprio 1
	v_mfma_f32_16x16x32_bf16 v[118:121], v[148:151], v[164:167], v[118:121]
	v_mfma_f32_16x16x32_bf16 v[114:117], v[156:159], v[164:167], v[114:117]
	v_mfma_f32_16x16x32_bf16 v[102:105], v[148:151], v[172:175], v[102:105]
	v_mfma_f32_16x16x32_bf16 v[98:101], v[156:159], v[172:175], v[98:101]
	v_mfma_f32_16x16x32_bf16 v[86:89], v[148:151], v[180:183], v[86:89]
	v_mfma_f32_16x16x32_bf16 v[82:85], v[156:159], v[180:183], v[82:85]
	v_mfma_f32_16x16x32_bf16 v[70:73], v[148:151], v[188:191], v[70:73]
	v_mfma_f32_16x16x32_bf16 v[66:69], v[156:159], v[188:191], v[66:69]
	v_mfma_f32_16x16x32_bf16 v[118:121], v[152:155], v[168:171], v[118:121]
	v_mfma_f32_16x16x32_bf16 v[114:117], v[160:163], v[168:171], v[114:117]
	v_mfma_f32_16x16x32_bf16 v[102:105], v[152:155], v[176:179], v[102:105]
	v_mfma_f32_16x16x32_bf16 v[98:101], v[160:163], v[176:179], v[98:101]
	v_mfma_f32_16x16x32_bf16 v[86:89], v[152:155], v[184:187], v[86:89]
	v_mfma_f32_16x16x32_bf16 v[82:85], v[160:163], v[184:187], v[82:85]
	v_mfma_f32_16x16x32_bf16 v[70:73], v[152:155], v[192:195], v[70:73]
	v_mfma_f32_16x16x32_bf16 v[66:69], v[160:163], v[192:195], v[66:69]
	s_barrier
	s_setprio 0
	s_add_i32 s29, s29, s42
	s_mov_b32 m0, s29
	global_load_lds_dwordx4 v0, s[20:21]
	s_add_i32 m0, s29, 0x2000
	s_add_u32 s52, s20, 0x20000
	s_addc_u32 s53, s21, 0
	s_add_i32 s29, s30, s42
	global_load_lds_dwordx4 v208, s[20:21]
	s_mov_b32 m0, s29
	s_nop 0
	global_load_lds_dwordx4 v0, s[52:53]
	s_add_i32 m0, s29, 0x2000
	s_nop 0
	global_load_lds_dwordx4 v208, s[52:53]
	s_mov_b32 m0, s93
	s_nop 0
	global_load_lds_dwordx4 v204, s[72:73]
	s_mov_b32 m0, s44
	s_nop 0
	global_load_lds_dwordx4 v206, s[72:73]
	ds_read_b128 v[164:167], v244 offset:16384
	ds_read_b128 v[168:171], v244 offset:17408
	ds_read_b128 v[172:175], v244 offset:18432
	ds_read_b128 v[176:179], v244 offset:19456
	ds_read_b128 v[180:183], v244 offset:20480
	ds_read_b128 v[184:187], v244 offset:21504
	ds_read_b128 v[188:191], v244 offset:22528
	ds_read_b128 v[192:195], v244 offset:23552
	s_waitcnt vmcnt(8) lgkmcnt(0)
	s_setprio 1
	s_barrier
	v_mfma_f32_16x16x32_bf16 v[62:65], v[132:135], v[164:167], v[62:65]
	v_mfma_f32_16x16x32_bf16 v[58:61], v[140:143], v[164:167], v[58:61]
	v_mfma_f32_16x16x32_bf16 v[46:49], v[132:135], v[172:175], v[46:49]
	v_mfma_f32_16x16x32_bf16 v[42:45], v[140:143], v[172:175], v[42:45]
	v_mfma_f32_16x16x32_bf16 v[30:33], v[132:135], v[180:183], v[30:33]
	v_mfma_f32_16x16x32_bf16 v[26:29], v[140:143], v[180:183], v[26:29]
	v_mfma_f32_16x16x32_bf16 v[14:17], v[132:135], v[188:191], v[14:17]
	v_mfma_f32_16x16x32_bf16 v[10:13], v[140:143], v[188:191], v[10:13]
	v_mfma_f32_16x16x32_bf16 v[62:65], v[136:139], v[168:171], v[62:65]
	v_mfma_f32_16x16x32_bf16 v[58:61], v[144:147], v[168:171], v[58:61]
	v_mfma_f32_16x16x32_bf16 v[46:49], v[136:139], v[176:179], v[46:49]
	v_mfma_f32_16x16x32_bf16 v[42:45], v[144:147], v[176:179], v[42:45]
	v_mfma_f32_16x16x32_bf16 v[30:33], v[136:139], v[184:187], v[30:33]
	v_mfma_f32_16x16x32_bf16 v[26:29], v[144:147], v[184:187], v[26:29]
	v_mfma_f32_16x16x32_bf16 v[14:17], v[136:139], v[192:195], v[14:17]
	v_mfma_f32_16x16x32_bf16 v[10:13], v[144:147], v[192:195], v[10:13]
	s_setprio 0
	s_setprio 1
	v_mfma_f32_16x16x32_bf16 v[54:57], v[148:151], v[164:167], v[54:57]
	v_mfma_f32_16x16x32_bf16 v[50:53], v[156:159], v[164:167], v[50:53]
	v_mfma_f32_16x16x32_bf16 v[38:41], v[148:151], v[172:175], v[38:41]
	v_mfma_f32_16x16x32_bf16 v[34:37], v[156:159], v[172:175], v[34:37]
	v_mfma_f32_16x16x32_bf16 v[22:25], v[148:151], v[180:183], v[22:25]
	v_mfma_f32_16x16x32_bf16 v[18:21], v[156:159], v[180:183], v[18:21]
	v_mfma_f32_16x16x32_bf16 v[6:9], v[148:151], v[188:191], v[6:9]
	v_mfma_f32_16x16x32_bf16 v[2:5], v[156:159], v[188:191], v[2:5]
	v_mfma_f32_16x16x32_bf16 v[54:57], v[152:155], v[168:171], v[54:57]
	v_mfma_f32_16x16x32_bf16 v[50:53], v[160:163], v[168:171], v[50:53]
	v_mfma_f32_16x16x32_bf16 v[38:41], v[152:155], v[176:179], v[38:41]
	v_mfma_f32_16x16x32_bf16 v[34:37], v[160:163], v[176:179], v[34:37]
	v_mfma_f32_16x16x32_bf16 v[22:25], v[152:155], v[184:187], v[22:25]
	v_mfma_f32_16x16x32_bf16 v[18:21], v[160:163], v[184:187], v[18:21]
	v_mfma_f32_16x16x32_bf16 v[6:9], v[152:155], v[192:195], v[6:9]
	v_mfma_f32_16x16x32_bf16 v[2:5], v[160:163], v[192:195], v[2:5]
	s_barrier
; #define PG8_STAGE(bufoff, gbase, voff) do { _Pragma("unroll") for (int _i = 0; _i < 2; ++_i) \
;         __builtin_amdgcn_global_load_lds((const gunsigned*)((const gchar*)(gbase) + (voff)[_i]), (LAS unsigned*)(lds + (bufoff) + ldsw + _i * 8192), 16, 0, 0); } while (0)
; #define PG8_LDA(dst, b, h) do { _Pragma("unroll") for (int m = 0; m < 4; ++m) _Pragma("unroll") for (int k = 0; k < 2; ++k) dst[m][k] = *(const LAS bf16x8*)(lds + PG8_SA(b, h) + aoff + m * 2048 + k * 1024); } while (0)
; #define PG8_LDB(dst, b, h) do { _Pragma("unroll") for (int n = 0; n < 2; ++n) _Pragma("unroll") for (int k = 0; k < 2; ++k) dst[n][k] = *(const LAS bf16x8*)(lds + PG8_SB(b, h) + boff + n * 2048 + k * 1024); } while (0)
; #define PG8_MMA(ai, bj, At, Bt) do { __builtin_amdgcn_s_setprio(1); _Pragma("unroll") for (int m = 0; m < 4; ++m) _Pragma("unroll") for (int n = 0; n < 2; ++n) _Pragma("unroll") for (int k = 0; k < 2; ++k) \
;         acc[ai][bj][m][n] = __builtin_amdgcn_mfma_f32_16x16x32_bf16(Bt[n][k], At[m][k], acc[ai][bj][m][n], 0, 0, 0); __builtin_amdgcn_s_setprio(0); } while (0)
; #define PG8_WAIT_V(n) asm volatile("s_waitcnt vmcnt(" #n ")" ::: "memory")
; #define PG8_WAIT_L(n) asm volatile("s_waitcnt lgkmcnt(" #n ")" ::: "memory")
; #define PG8_BAR __builtin_amdgcn_s_barrier()
; #define PG8_SCHED __builtin_amdgcn_sched_barrier(0)
; template <class Epi, class Sched>
; __device__ __forceinline__ void gemm_phase(LAS unsigned char* lds, const int tid, const Gemm g, const Sched& S, const Epi& E) {
;     ...
;             PG8_LDB(B0, 1, 0); PG8_LDB(B1, 1, 1); PG8_SCHED; PG8_LDA(At, 1, 0); PG8_STAGE(PG8_SA(0, 1), a2 + hstep, voffA);
;             PG8_WAIT_V(8); PG8_WAIT_L(0); PG8_BAR; PG8_MMA(0, 0, At, B0); PG8_MMA(0, 1, At, B1); PG8_BAR; PG8_SCHED;
;             PG8_LDA(At, 1, 1); PG8_STAGE(PG8_SB(1, 0), b3, voffB); PG8_STAGE(PG8_SB(1, 1), b3 + hstep, voffB); PG8_STAGE(PG8_SA(1, 0), a3, voffA);
;             PG8_WAIT_V(8); PG8_WAIT_L(0); PG8_BAR; PG8_MMA(1, 0, At, B0); PG8_MMA(1, 1, At, B1); PG8_BAR; PG8_SCHED;
;         }
;         if (wr == 0) PG8_BAR;
	s_setprio 0
	s_add_i32 s29, 0, 0x18000
	v_add_u32_e32 v126, s29, v242
	s_add_i32 s30, 0, 0x1c000
	s_add_u32 s52, s72, 0x20000
	s_addc_u32 s53, s73, 0
	s_mov_b32 m0, s45
	global_load_lds_dwordx4 v204, s[52:53]
	s_mov_b32 m0, s46
	s_nop 0
	global_load_lds_dwordx4 v206, s[52:53]
	ds_read_b128 v[132:135], v126
	ds_read_b128 v[136:139], v126 offset:1024
	ds_read_b128 v[140:143], v126 offset:2048
	ds_read_b128 v[144:147], v126 offset:3072
	v_add_u32_e32 v126, s30, v242
	ds_read_b128 v[148:151], v126
	ds_read_b128 v[152:155], v126 offset:1024
	ds_read_b128 v[156:159], v126 offset:2048
	ds_read_b128 v[160:163], v126 offset:3072
	ds_read_b128 v[164:167], v244 offset:32768
	ds_read_b128 v[168:171], v244 offset:33792
	ds_read_b128 v[172:175], v244 offset:34816
	ds_read_b128 v[176:179], v244 offset:35840
	ds_read_b128 v[180:183], v244 offset:36864
	ds_read_b128 v[184:187], v244 offset:37888
	ds_read_b128 v[188:191], v244 offset:38912
	ds_read_b128 v[192:195], v244 offset:39936
	s_waitcnt vmcnt(8) lgkmcnt(0)
	s_setprio 1
	s_barrier
	v_mfma_f32_16x16x32_bf16 v[126:129], v[132:135], v[164:167], v[128:131]
	v_mfma_f32_16x16x32_bf16 v[122:125], v[140:143], v[164:167], v[122:125]
	v_mfma_f32_16x16x32_bf16 v[110:113], v[132:135], v[172:175], v[110:113]
	v_mfma_f32_16x16x32_bf16 v[106:109], v[140:143], v[172:175], v[106:109]
	v_mfma_f32_16x16x32_bf16 v[94:97], v[132:135], v[180:183], v[94:97]
	v_mfma_f32_16x16x32_bf16 v[90:93], v[140:143], v[180:183], v[90:93]
	v_mfma_f32_16x16x32_bf16 v[78:81], v[132:135], v[188:191], v[78:81]
	v_mfma_f32_16x16x32_bf16 v[74:77], v[140:143], v[188:191], v[74:77]
	v_mfma_f32_16x16x32_bf16 v[128:131], v[136:139], v[168:171], v[126:129]
	v_mfma_f32_16x16x32_bf16 v[124:127], v[144:147], v[168:171], v[122:125]
	v_mfma_f32_16x16x32_bf16 v[110:113], v[136:139], v[176:179], v[110:113]
	v_mfma_f32_16x16x32_bf16 v[106:109], v[144:147], v[176:179], v[106:109]
	v_mfma_f32_16x16x32_bf16 v[94:97], v[136:139], v[184:187], v[94:97]
	v_mfma_f32_16x16x32_bf16 v[90:93], v[144:147], v[184:187], v[90:93]
	v_mfma_f32_16x16x32_bf16 v[78:81], v[136:139], v[192:195], v[78:81]
	v_mfma_f32_16x16x32_bf16 v[74:77], v[144:147], v[192:195], v[74:77]
	s_setprio 0
	s_setprio 1
	v_mfma_f32_16x16x32_bf16 v[118:121], v[148:151], v[164:167], v[118:121]
	v_mfma_f32_16x16x32_bf16 v[114:117], v[156:159], v[164:167], v[114:117]
	v_mfma_f32_16x16x32_bf16 v[102:105], v[148:151], v[172:175], v[102:105]
	v_mfma_f32_16x16x32_bf16 v[98:101], v[156:159], v[172:175], v[98:101]
	v_mfma_f32_16x16x32_bf16 v[86:89], v[148:151], v[180:183], v[86:89]
	v_mfma_f32_16x16x32_bf16 v[82:85], v[156:159], v[180:183], v[82:85]
	v_mfma_f32_16x16x32_bf16 v[70:73], v[148:151], v[188:191], v[70:73]
	v_mfma_f32_16x16x32_bf16 v[66:69], v[156:159], v[188:191], v[66:69]
	v_mfma_f32_16x16x32_bf16 v[118:121], v[152:155], v[168:171], v[118:121]
	v_mfma_f32_16x16x32_bf16 v[114:117], v[160:163], v[168:171], v[114:117]
	v_mfma_f32_16x16x32_bf16 v[102:105], v[152:155], v[176:179], v[102:105]
	v_mfma_f32_16x16x32_bf16 v[98:101], v[160:163], v[176:179], v[98:101]
	v_mfma_f32_16x16x32_bf16 v[86:89], v[152:155], v[184:187], v[86:89]
	v_mfma_f32_16x16x32_bf16 v[82:85], v[160:163], v[184:187], v[82:85]
	v_mfma_f32_16x16x32_bf16 v[70:73], v[152:155], v[192:195], v[70:73]
	v_mfma_f32_16x16x32_bf16 v[66:69], v[160:163], v[192:195], v[66:69]
	s_barrier
	s_setprio 0
	s_add_i32 s29, s29, s42
	s_mov_b32 m0, s29
	ds_read_b128 v[164:167], v244 offset:49152
	global_load_lds_dwordx4 v201, s[20:21]
	s_add_i32 m0, s29, 0x2000
	s_add_i32 s29, s30, s42
	global_load_lds_dwordx4 v215, s[20:21]
	s_add_u32 s20, s20, 0x20080
	s_addc_u32 s21, s21, 0
	s_mov_b32 m0, s29
	s_nop 0
	global_load_lds_dwordx4 v0, s[20:21]
	s_add_i32 m0, s29, 0x2000
	s_nop 0
	global_load_lds_dwordx4 v208, s[20:21]
	s_mov_b32 m0, s47
	s_nop 0
	global_load_lds_dwordx4 v217, s[72:73]
	s_mov_b32 m0, s48
	s_nop 0
	global_load_lds_dwordx4 v219, s[72:73]
	ds_read_b128 v[168:171], v244 offset:50176
	ds_read_b128 v[172:175], v244 offset:51200
	ds_read_b128 v[176:179], v244 offset:52224
	ds_read_b128 v[180:183], v244 offset:53248
	ds_read_b128 v[184:187], v244 offset:54272
	ds_read_b128 v[188:191], v244 offset:55296
	ds_read_b128 v[192:195], v244 offset:56320
	s_waitcnt vmcnt(8) lgkmcnt(0)
	s_setprio 1
	s_barrier
	v_mfma_f32_16x16x32_bf16 v[62:65], v[132:135], v[164:167], v[62:65]
	v_mfma_f32_16x16x32_bf16 v[58:61], v[140:143], v[164:167], v[58:61]
	v_mfma_f32_16x16x32_bf16 v[46:49], v[132:135], v[172:175], v[46:49]
	v_mfma_f32_16x16x32_bf16 v[42:45], v[140:143], v[172:175], v[42:45]
	v_mfma_f32_16x16x32_bf16 v[30:33], v[132:135], v[180:183], v[30:33]
	v_mfma_f32_16x16x32_bf16 v[26:29], v[140:143], v[180:183], v[26:29]
	v_mfma_f32_16x16x32_bf16 v[14:17], v[132:135], v[188:191], v[14:17]
	v_mfma_f32_16x16x32_bf16 v[10:13], v[140:143], v[188:191], v[10:13]
	v_mfma_f32_16x16x32_bf16 v[62:65], v[136:139], v[168:171], v[62:65]
	v_mfma_f32_16x16x32_bf16 v[58:61], v[144:147], v[168:171], v[58:61]
	v_mfma_f32_16x16x32_bf16 v[46:49], v[136:139], v[176:179], v[46:49]
	v_mfma_f32_16x16x32_bf16 v[42:45], v[144:147], v[176:179], v[42:45]
	v_mfma_f32_16x16x32_bf16 v[30:33], v[136:139], v[184:187], v[30:33]
	v_mfma_f32_16x16x32_bf16 v[26:29], v[144:147], v[184:187], v[26:29]
	v_mfma_f32_16x16x32_bf16 v[14:17], v[136:139], v[192:195], v[14:17]
	v_mfma_f32_16x16x32_bf16 v[10:13], v[144:147], v[192:195], v[10:13]
	s_setprio 0
	s_setprio 1
	v_mfma_f32_16x16x32_bf16 v[54:57], v[148:151], v[164:167], v[54:57]
	v_mfma_f32_16x16x32_bf16 v[50:53], v[156:159], v[164:167], v[50:53]
	v_mfma_f32_16x16x32_bf16 v[38:41], v[148:151], v[172:175], v[38:41]
	v_mfma_f32_16x16x32_bf16 v[34:37], v[156:159], v[172:175], v[34:37]
	v_mfma_f32_16x16x32_bf16 v[22:25], v[148:151], v[180:183], v[22:25]
	v_mfma_f32_16x16x32_bf16 v[18:21], v[156:159], v[180:183], v[18:21]
	v_mfma_f32_16x16x32_bf16 v[6:9], v[148:151], v[188:191], v[6:9]
	v_mfma_f32_16x16x32_bf16 v[2:5], v[156:159], v[188:191], v[2:5]
	v_mfma_f32_16x16x32_bf16 v[54:57], v[152:155], v[168:171], v[54:57]
	v_mfma_f32_16x16x32_bf16 v[50:53], v[160:163], v[168:171], v[50:53]
	v_mfma_f32_16x16x32_bf16 v[38:41], v[152:155], v[176:179], v[38:41]
	v_mfma_f32_16x16x32_bf16 v[34:37], v[160:163], v[176:179], v[34:37]
	v_mfma_f32_16x16x32_bf16 v[22:25], v[152:155], v[184:187], v[22:25]
	v_mfma_f32_16x16x32_bf16 v[18:21], v[160:163], v[184:187], v[18:21]
	v_mfma_f32_16x16x32_bf16 v[6:9], v[152:155], v[192:195], v[6:9]
	v_mfma_f32_16x16x32_bf16 v[2:5], v[160:163], v[192:195], v[2:5]
	s_barrier
	s_setprio 0
	s_add_i32 s51, s51, 2
	s_add_u32 s24, s24, 0x100
	s_addc_u32 s31, s31, 0
	s_add_u32 s16, s16, 0x100
	s_addc_u32 s17, s17, 0
	s_cmp_gt_u32 s51, 5
	s_cbranch_scc0 .LBB0_444
	s_and_b64 vcc, exec, s[10:11]
	s_cbranch_vccz .LBB0_447
	s_barrier

; #define PG8_STAGE(bufoff, gbase, voff) do { _Pragma("unroll") for (int _i = 0; _i < 2; ++_i) \
;         __builtin_amdgcn_global_load_lds((const gunsigned*)((const gchar*)(gbase) + (voff)[_i]), (LAS unsigned*)(lds + (bufoff) + ldsw + _i * 8192), 16, 0, 0); } while (0)
; #define PG8_LDA(dst, b, h) do { _Pragma("unroll") for (int m = 0; m < 4; ++m) _Pragma("unroll") for (int k = 0; k < 2; ++k) dst[m][k] = *(const LAS bf16x8*)(lds + PG8_SA(b, h) + aoff + m * 2048 + k * 1024); } while (0)
; #define PG8_LDB(dst, b, h) do { _Pragma("unroll") for (int n = 0; n < 2; ++n) _Pragma("unroll") for (int k = 0; k < 2; ++k) dst[n][k] = *(const LAS bf16x8*)(lds + PG8_SB(b, h) + boff + n * 2048 + k * 1024); } while (0)
; #define PG8_MMA(ai, bj, At, Bt) do { __builtin_amdgcn_s_setprio(1); _Pragma("unroll") for (int m = 0; m < 4; ++m) _Pragma("unroll") for (int n = 0; n < 2; ++n) _Pragma("unroll") for (int k = 0; k < 2; ++k) \
;         acc[ai][bj][m][n] = __builtin_amdgcn_mfma_f32_16x16x32_bf16(Bt[n][k], At[m][k], acc[ai][bj][m][n], 0, 0, 0); __builtin_amdgcn_s_setprio(0); } while (0)
; #define PG8_WAIT_V(n) asm volatile("s_waitcnt vmcnt(" #n ")" ::: "memory")
; #define PG8_WAIT_L(n) asm volatile("s_waitcnt lgkmcnt(" #n ")" ::: "memory")
; #define PG8_BAR __builtin_amdgcn_s_barrier()
; #define PG8_SCHED __builtin_amdgcn_sched_barrier(0)
; template <class Epi, class Sched>
; __device__ __forceinline__ void gemm_phase(LAS unsigned char* lds, const int tid, const Gemm g, const Sched& S, const Epi& E) {
;     ...
;         for (int t = 0; t < nt; t += 2) {
;             const bool last = (t == nt - 2);
;             const gchar* a1 = cA + (size_t)(t + 1) * kstep;
;             const gchar* a2 = last ? nA : cA + (size_t)(t + 2) * kstep; const gchar* b2 = last ? nB : cB + (size_t)(t + 2) * kstep;
;             const gchar* a3 = a2 + kstep; const gchar* b3 = b2 + kstep;
;             PG8_LDB(B0, 0, 0); PG8_LDB(B1, 0, 1); PG8_SCHED; PG8_LDA(At, 0, 0); PG8_STAGE(PG8_SA(1, 1), a1 + hstep, voffA);
;             PG8_WAIT_V(8); PG8_WAIT_L(0); PG8_BAR; PG8_MMA(0, 0, At, B0); PG8_MMA(0, 1, At, B1); PG8_BAR; PG8_SCHED;
;             PG8_LDA(At, 0, 1); PG8_STAGE(PG8_SB(0, 0), b2, voffB); PG8_STAGE(PG8_SB(0, 1), b2 + hstep, voffB); PG8_STAGE(PG8_SA(0, 0), a2, voffA);
;             PG8_WAIT_V(8); PG8_WAIT_L(0); PG8_BAR; PG8_MMA(1, 0, At, B0); PG8_MMA(1, 1, At, B1); PG8_BAR; PG8_SCHED;
.LBB0_559:
	s_add_u32 s20, s60, 0xfffc0080
	s_addc_u32 s21, s61, -1
	s_add_i32 s29, 0, 0x10000
	s_cmp_eq_u32 s46, 12
	s_cselect_b32 s63, s9, s21
	s_cselect_b32 s62, s42, s20
	s_cselect_b32 s21, s7, s45
	s_cselect_b32 s20, s43, s44
	s_add_i32 s30, 0, 0x14000
	s_add_i32 m0, s34, 0xc000
	global_load_lds_dwordx4 v142, s[60:61]
	s_add_i32 m0, s34, 0xe000
	s_nop 0
	global_load_lds_dwordx4 v140, s[60:61]
	v_add_u32_e32 v152, s29, v165
	v_add_u32_e32 v160, s30, v165
	ds_read_b128 v[130:133], v152
	ds_read_b128 v[144:147], v152 offset:1024
	ds_read_b128 v[148:151], v152 offset:2048
	ds_read_b128 v[152:155], v152 offset:3072
	ds_read_b128 v[156:159], v160
	ds_read_b128 v[170:173], v160 offset:1024
	ds_read_b128 v[174:177], v160 offset:2048
	ds_read_b128 v[178:181], v160 offset:3072
	ds_read_b128 v[182:185], v169
	ds_read_b128 v[186:189], v169 offset:1024
	ds_read_b128 v[190:193], v169 offset:2048
	ds_read_b128 v[204:207], v169 offset:3072
	ds_read_b128 v[210:213], v169 offset:4096
	ds_read_b128 v[214:217], v169 offset:5120
	ds_read_b128 v[218:221], v169 offset:6144
	ds_read_b128 v[222:225], v169 offset:7168
	s_waitcnt vmcnt(8) lgkmcnt(0)
	s_setprio 1
	s_barrier
	v_mfma_f32_16x16x32_bf16 v[126:129], v[130:133], v[182:185], v[126:129]
	v_mfma_f32_16x16x32_bf16 v[122:125], v[148:151], v[182:185], v[122:125]
	v_mfma_f32_16x16x32_bf16 v[118:121], v[130:133], v[190:193], v[118:121]
	v_mfma_f32_16x16x32_bf16 v[110:113], v[148:151], v[190:193], v[110:113]
	v_mfma_f32_16x16x32_bf16 v[102:105], v[130:133], v[210:213], v[102:105]
	v_mfma_f32_16x16x32_bf16 v[94:97], v[148:151], v[210:213], v[94:97]
	v_mfma_f32_16x16x32_bf16 v[86:89], v[130:133], v[218:221], v[86:89]
	v_mfma_f32_16x16x32_bf16 v[78:81], v[148:151], v[218:221], v[78:81]
	v_mfma_f32_16x16x32_bf16 v[126:129], v[144:147], v[186:189], v[126:129]
	v_mfma_f32_16x16x32_bf16 v[122:125], v[152:155], v[186:189], v[122:125]
	v_mfma_f32_16x16x32_bf16 v[118:121], v[144:147], v[204:207], v[118:121]
	v_mfma_f32_16x16x32_bf16 v[110:113], v[152:155], v[204:207], v[110:113]
	v_mfma_f32_16x16x32_bf16 v[102:105], v[144:147], v[214:217], v[102:105]
	v_mfma_f32_16x16x32_bf16 v[94:97], v[152:155], v[214:217], v[94:97]
	v_mfma_f32_16x16x32_bf16 v[86:89], v[144:147], v[222:225], v[86:89]
	v_mfma_f32_16x16x32_bf16 v[78:81], v[152:155], v[222:225], v[78:81]
	s_setprio 0
	s_setprio 1
	v_mfma_f32_16x16x32_bf16 v[114:117], v[156:159], v[182:185], v[114:117]
	v_mfma_f32_16x16x32_bf16 v[106:109], v[174:177], v[182:185], v[106:109]
	v_mfma_f32_16x16x32_bf16 v[98:101], v[156:159], v[190:193], v[98:101]
	v_mfma_f32_16x16x32_bf16 v[90:93], v[174:177], v[190:193], v[90:93]
	v_mfma_f32_16x16x32_bf16 v[82:85], v[156:159], v[210:213], v[82:85]
	v_mfma_f32_16x16x32_bf16 v[74:77], v[174:177], v[210:213], v[74:77]
	v_mfma_f32_16x16x32_bf16 v[70:73], v[156:159], v[218:221], v[70:73]
	v_mfma_f32_16x16x32_bf16 v[66:69], v[174:177], v[218:221], v[66:69]
	v_mfma_f32_16x16x32_bf16 v[114:117], v[170:173], v[186:189], v[114:117]
	v_mfma_f32_16x16x32_bf16 v[106:109], v[178:181], v[186:189], v[106:109]
	v_mfma_f32_16x16x32_bf16 v[98:101], v[170:173], v[204:207], v[98:101]
	v_mfma_f32_16x16x32_bf16 v[90:93], v[178:181], v[204:207], v[90:93]
	v_mfma_f32_16x16x32_bf16 v[82:85], v[170:173], v[214:217], v[82:85]
	v_mfma_f32_16x16x32_bf16 v[74:77], v[178:181], v[214:217], v[74:77]
	v_mfma_f32_16x16x32_bf16 v[70:73], v[170:173], v[222:225], v[70:73]
	v_mfma_f32_16x16x32_bf16 v[66:69], v[178:181], v[222:225], v[66:69]
	s_barrier
	s_setprio 0
	s_add_i32 s29, s29, s12
	s_mov_b32 m0, s29
	global_load_lds_dwordx4 v0, s[20:21]
	s_add_i32 m0, s29, 0x2000
	s_add_u32 s48, s20, 0x40000
	s_addc_u32 s49, s21, 0
	s_add_i32 s29, s30, s12
	global_load_lds_dwordx4 v134, s[20:21]
	s_mov_b32 m0, s29
	s_nop 0
	global_load_lds_dwordx4 v0, s[48:49]
	s_add_i32 m0, s29, 0x2000
	s_nop 0
	global_load_lds_dwordx4 v134, s[48:49]
	s_mov_b32 m0, s34
	s_nop 0
	global_load_lds_dwordx4 v138, s[62:63]
	s_mov_b32 m0, s35
	s_nop 0
	global_load_lds_dwordx4 v136, s[62:63]
	ds_read_b128 v[182:185], v169 offset:16384
	ds_read_b128 v[186:189], v169 offset:17408
	ds_read_b128 v[190:193], v169 offset:18432
	ds_read_b128 v[204:207], v169 offset:19456
	ds_read_b128 v[210:213], v169 offset:20480
	ds_read_b128 v[214:217], v169 offset:21504
	ds_read_b128 v[218:221], v169 offset:22528
	ds_read_b128 v[222:225], v169 offset:23552
	s_waitcnt vmcnt(8) lgkmcnt(0)
	s_setprio 1
	s_barrier
	v_mfma_f32_16x16x32_bf16 v[62:65], v[130:133], v[182:185], v[62:65]
	v_mfma_f32_16x16x32_bf16 v[58:61], v[148:151], v[182:185], v[58:61]
	v_mfma_f32_16x16x32_bf16 v[54:57], v[130:133], v[190:193], v[54:57]
	v_mfma_f32_16x16x32_bf16 v[46:49], v[148:151], v[190:193], v[46:49]
	v_mfma_f32_16x16x32_bf16 v[38:41], v[130:133], v[210:213], v[38:41]
	v_mfma_f32_16x16x32_bf16 v[30:33], v[148:151], v[210:213], v[30:33]
	v_mfma_f32_16x16x32_bf16 v[22:25], v[130:133], v[218:221], v[22:25]
	v_mfma_f32_16x16x32_bf16 v[14:17], v[148:151], v[218:221], v[14:17]
	v_mfma_f32_16x16x32_bf16 v[62:65], v[144:147], v[186:189], v[62:65]
	v_mfma_f32_16x16x32_bf16 v[58:61], v[152:155], v[186:189], v[58:61]
	v_mfma_f32_16x16x32_bf16 v[54:57], v[144:147], v[204:207], v[54:57]
	v_mfma_f32_16x16x32_bf16 v[46:49], v[152:155], v[204:207], v[46:49]
	v_mfma_f32_16x16x32_bf16 v[38:41], v[144:147], v[214:217], v[38:41]
	v_mfma_f32_16x16x32_bf16 v[30:33], v[152:155], v[214:217], v[30:33]
	v_mfma_f32_16x16x32_bf16 v[22:25], v[144:147], v[222:225], v[22:25]
	v_mfma_f32_16x16x32_bf16 v[14:17], v[152:155], v[222:225], v[14:17]
	s_setprio 0
	s_setprio 1
	v_mfma_f32_16x16x32_bf16 v[50:53], v[156:159], v[182:185], v[50:53]
	v_mfma_f32_16x16x32_bf16 v[42:45], v[174:177], v[182:185], v[42:45]
	v_mfma_f32_16x16x32_bf16 v[34:37], v[156:159], v[190:193], v[34:37]
	v_mfma_f32_16x16x32_bf16 v[26:29], v[174:177], v[190:193], v[26:29]
	v_mfma_f32_16x16x32_bf16 v[18:21], v[156:159], v[210:213], v[18:21]
	v_mfma_f32_16x16x32_bf16 v[10:13], v[174:177], v[210:213], v[10:13]
	v_mfma_f32_16x16x32_bf16 v[6:9], v[156:159], v[218:221], v[6:9]
	v_mfma_f32_16x16x32_bf16 v[2:5], v[174:177], v[218:221], v[2:5]
	v_mfma_f32_16x16x32_bf16 v[50:53], v[170:173], v[186:189], v[50:53]
	v_mfma_f32_16x16x32_bf16 v[42:45], v[178:181], v[186:189], v[42:45]
	v_mfma_f32_16x16x32_bf16 v[34:37], v[170:173], v[204:207], v[34:37]
	v_mfma_f32_16x16x32_bf16 v[26:29], v[178:181], v[204:207], v[26:29]
	v_mfma_f32_16x16x32_bf16 v[18:21], v[170:173], v[214:217], v[18:21]
	v_mfma_f32_16x16x32_bf16 v[10:13], v[178:181], v[214:217], v[10:13]
	v_mfma_f32_16x16x32_bf16 v[6:9], v[170:173], v[222:225], v[6:9]
	v_mfma_f32_16x16x32_bf16 v[2:5], v[178:181], v[222:225], v[2:5]
	s_barrier
; #define PG8_STAGE(bufoff, gbase, voff) do { _Pragma("unroll") for (int _i = 0; _i < 2; ++_i) \
;         __builtin_amdgcn_global_load_lds((const gunsigned*)((const gchar*)(gbase) + (voff)[_i]), (LAS unsigned*)(lds + (bufoff) + ldsw + _i * 8192), 16, 0, 0); } while (0)
; #define PG8_LDA(dst, b, h) do { _Pragma("unroll") for (int m = 0; m < 4; ++m) _Pragma("unroll") for (int k = 0; k < 2; ++k) dst[m][k] = *(const LAS bf16x8*)(lds + PG8_SA(b, h) + aoff + m * 2048 + k * 1024); } while (0)
; #define PG8_LDB(dst, b, h) do { _Pragma("unroll") for (int n = 0; n < 2; ++n) _Pragma("unroll") for (int k = 0; k < 2; ++k) dst[n][k] = *(const LAS bf16x8*)(lds + PG8_SB(b, h) + boff + n * 2048 + k * 1024); } while (0)
; #define PG8_MMA(ai, bj, At, Bt) do { __builtin_amdgcn_s_setprio(1); _Pragma("unroll") for (int m = 0; m < 4; ++m) _Pragma("unroll") for (int n = 0; n < 2; ++n) _Pragma("unroll") for (int k = 0; k < 2; ++k) \
;         acc[ai][bj][m][n] = __builtin_amdgcn_mfma_f32_16x16x32_bf16(Bt[n][k], At[m][k], acc[ai][bj][m][n], 0, 0, 0); __builtin_amdgcn_s_setprio(0); } while (0)
; #define PG8_WAIT_V(n) asm volatile("s_waitcnt vmcnt(" #n ")" ::: "memory")
; #define PG8_WAIT_L(n) asm volatile("s_waitcnt lgkmcnt(" #n ")" ::: "memory")
; #define PG8_BAR __builtin_amdgcn_s_barrier()
; #define PG8_SCHED __builtin_amdgcn_sched_barrier(0)
; template <class Epi, class Sched>
; __device__ __forceinline__ void gemm_phase(LAS unsigned char* lds, const int tid, const Gemm g, const Sched& S, const Epi& E) {
;     ...
;             PG8_LDB(B0, 1, 0); PG8_LDB(B1, 1, 1); PG8_SCHED; PG8_LDA(At, 1, 0); PG8_STAGE(PG8_SA(0, 1), a2 + hstep, voffA);
;             PG8_WAIT_V(8); PG8_WAIT_L(0); PG8_BAR; PG8_MMA(0, 0, At, B0); PG8_MMA(0, 1, At, B1); PG8_BAR; PG8_SCHED;
;             PG8_LDA(At, 1, 1); PG8_STAGE(PG8_SB(1, 0), b3, voffB); PG8_STAGE(PG8_SB(1, 1), b3 + hstep, voffB); PG8_STAGE(PG8_SA(1, 0), a3, voffA);
;             PG8_WAIT_V(8); PG8_WAIT_L(0); PG8_BAR; PG8_MMA(1, 0, At, B0); PG8_MMA(1, 1, At, B1); PG8_BAR; PG8_SCHED;
;         }
;         if (wr == 0) PG8_BAR;
	s_setprio 0
	s_add_i32 s29, 0, 0x18000
	s_add_i32 s30, 0, 0x1c000
	s_add_u32 s48, s62, 0x40000
	s_addc_u32 s49, s63, 0
	s_mov_b32 m0, s36
	global_load_lds_dwordx4 v138, s[48:49]
	s_mov_b32 m0, s37
	s_nop 0
	global_load_lds_dwordx4 v136, s[48:49]
	v_add_u32_e32 v152, s29, v165
	v_add_u32_e32 v162, s30, v165
	ds_read_b128 v[130:133], v152
	ds_read_b128 v[144:147], v152 offset:1024
	ds_read_b128 v[148:151], v152 offset:2048
	ds_read_b128 v[152:155], v152 offset:3072
	ds_read_b128 v[156:159], v162
	ds_read_b128 v[170:173], v162 offset:1024
	ds_read_b128 v[174:177], v162 offset:2048
	ds_read_b128 v[178:181], v162 offset:3072
	ds_read_b128 v[182:185], v169 offset:32768
	ds_read_b128 v[186:189], v169 offset:33792
	ds_read_b128 v[190:193], v169 offset:34816
	ds_read_b128 v[204:207], v169 offset:35840
	ds_read_b128 v[210:213], v169 offset:36864
	ds_read_b128 v[214:217], v169 offset:37888
	ds_read_b128 v[218:221], v169 offset:38912
	ds_read_b128 v[222:225], v169 offset:39936
	s_waitcnt vmcnt(8) lgkmcnt(0)
	s_setprio 1
	s_barrier
	v_mfma_f32_16x16x32_bf16 v[126:129], v[130:133], v[182:185], v[126:129]
	v_mfma_f32_16x16x32_bf16 v[122:125], v[148:151], v[182:185], v[122:125]
	v_mfma_f32_16x16x32_bf16 v[118:121], v[130:133], v[190:193], v[118:121]
	v_mfma_f32_16x16x32_bf16 v[110:113], v[148:151], v[190:193], v[110:113]
	v_mfma_f32_16x16x32_bf16 v[102:105], v[130:133], v[210:213], v[102:105]
	v_mfma_f32_16x16x32_bf16 v[94:97], v[148:151], v[210:213], v[94:97]
	v_mfma_f32_16x16x32_bf16 v[86:89], v[130:133], v[218:221], v[86:89]
	v_mfma_f32_16x16x32_bf16 v[78:81], v[148:151], v[218:221], v[78:81]
	v_mfma_f32_16x16x32_bf16 v[126:129], v[144:147], v[186:189], v[126:129]
	v_mfma_f32_16x16x32_bf16 v[122:125], v[152:155], v[186:189], v[122:125]
	v_mfma_f32_16x16x32_bf16 v[118:121], v[144:147], v[204:207], v[118:121]
	v_mfma_f32_16x16x32_bf16 v[110:113], v[152:155], v[204:207], v[110:113]
	v_mfma_f32_16x16x32_bf16 v[102:105], v[144:147], v[214:217], v[102:105]
	v_mfma_f32_16x16x32_bf16 v[94:97], v[152:155], v[214:217], v[94:97]
	v_mfma_f32_16x16x32_bf16 v[86:89], v[144:147], v[222:225], v[86:89]
	v_mfma_f32_16x16x32_bf16 v[78:81], v[152:155], v[222:225], v[78:81]
	s_setprio 0
	s_setprio 1
	v_mfma_f32_16x16x32_bf16 v[114:117], v[156:159], v[182:185], v[114:117]
	v_mfma_f32_16x16x32_bf16 v[106:109], v[174:177], v[182:185], v[106:109]
	v_mfma_f32_16x16x32_bf16 v[98:101], v[156:159], v[190:193], v[98:101]
	v_mfma_f32_16x16x32_bf16 v[90:93], v[174:177], v[190:193], v[90:93]
	v_mfma_f32_16x16x32_bf16 v[82:85], v[156:159], v[210:213], v[82:85]
	v_mfma_f32_16x16x32_bf16 v[74:77], v[174:177], v[210:213], v[74:77]
	v_mfma_f32_16x16x32_bf16 v[70:73], v[156:159], v[218:221], v[70:73]
	v_mfma_f32_16x16x32_bf16 v[66:69], v[174:177], v[218:221], v[66:69]
	v_mfma_f32_16x16x32_bf16 v[114:117], v[170:173], v[186:189], v[114:117]
	v_mfma_f32_16x16x32_bf16 v[106:109], v[178:181], v[186:189], v[106:109]
	v_mfma_f32_16x16x32_bf16 v[98:101], v[170:173], v[204:207], v[98:101]
	v_mfma_f32_16x16x32_bf16 v[90:93], v[178:181], v[204:207], v[90:93]
	v_mfma_f32_16x16x32_bf16 v[82:85], v[170:173], v[214:217], v[82:85]
	v_mfma_f32_16x16x32_bf16 v[74:77], v[178:181], v[214:217], v[74:77]
	v_mfma_f32_16x16x32_bf16 v[70:73], v[170:173], v[222:225], v[70:73]
	v_mfma_f32_16x16x32_bf16 v[66:69], v[178:181], v[222:225], v[66:69]
	s_barrier
	s_setprio 0
	s_add_i32 s29, s29, s12
	s_mov_b32 m0, s29
	ds_read_b128 v[182:185], v169 offset:49152
	global_load_lds_dwordx4 v161, s[20:21]
	s_add_i32 m0, s29, 0x2000
	s_add_i32 s29, s30, s12
	global_load_lds_dwordx4 v195, s[20:21]
	s_add_u32 s20, s20, 0x40080
	s_addc_u32 s21, s21, 0
	s_mov_b32 m0, s29
	s_nop 0
	global_load_lds_dwordx4 v0, s[20:21]
	s_add_i32 m0, s29, 0x2000
	s_nop 0
	global_load_lds_dwordx4 v134, s[20:21]
	s_mov_b32 m0, s38
	s_nop 0
	global_load_lds_dwordx4 v201, s[62:63]
	s_mov_b32 m0, s39
	s_nop 0
	global_load_lds_dwordx4 v227, s[62:63]
	ds_read_b128 v[186:189], v169 offset:50176
	ds_read_b128 v[190:193], v169 offset:51200
	ds_read_b128 v[204:207], v169 offset:52224
	ds_read_b128 v[210:213], v169 offset:53248
	ds_read_b128 v[214:217], v169 offset:54272
	ds_read_b128 v[218:221], v169 offset:55296
	ds_read_b128 v[222:225], v169 offset:56320
	s_waitcnt vmcnt(8) lgkmcnt(0)
	s_setprio 1
	s_barrier
	v_mfma_f32_16x16x32_bf16 v[62:65], v[130:133], v[182:185], v[62:65]
	v_mfma_f32_16x16x32_bf16 v[58:61], v[148:151], v[182:185], v[58:61]
	v_mfma_f32_16x16x32_bf16 v[54:57], v[130:133], v[190:193], v[54:57]
	v_mfma_f32_16x16x32_bf16 v[46:49], v[148:151], v[190:193], v[46:49]
	v_mfma_f32_16x16x32_bf16 v[38:41], v[130:133], v[210:213], v[38:41]
	v_mfma_f32_16x16x32_bf16 v[30:33], v[148:151], v[210:213], v[30:33]
	v_mfma_f32_16x16x32_bf16 v[22:25], v[130:133], v[218:221], v[22:25]
	v_mfma_f32_16x16x32_bf16 v[14:17], v[148:151], v[218:221], v[14:17]
	v_mfma_f32_16x16x32_bf16 v[62:65], v[144:147], v[186:189], v[62:65]
	v_mfma_f32_16x16x32_bf16 v[58:61], v[152:155], v[186:189], v[58:61]
	v_mfma_f32_16x16x32_bf16 v[54:57], v[144:147], v[204:207], v[54:57]
	v_mfma_f32_16x16x32_bf16 v[46:49], v[152:155], v[204:207], v[46:49]
	v_mfma_f32_16x16x32_bf16 v[38:41], v[144:147], v[214:217], v[38:41]
	v_mfma_f32_16x16x32_bf16 v[30:33], v[152:155], v[214:217], v[30:33]
	v_mfma_f32_16x16x32_bf16 v[22:25], v[144:147], v[222:225], v[22:25]
	v_mfma_f32_16x16x32_bf16 v[14:17], v[152:155], v[222:225], v[14:17]
	s_setprio 0
	s_setprio 1
	v_mfma_f32_16x16x32_bf16 v[50:53], v[156:159], v[182:185], v[50:53]
	v_mfma_f32_16x16x32_bf16 v[42:45], v[174:177], v[182:185], v[42:45]
	v_mfma_f32_16x16x32_bf16 v[34:37], v[156:159], v[190:193], v[34:37]
	v_mfma_f32_16x16x32_bf16 v[26:29], v[174:177], v[190:193], v[26:29]
	v_mfma_f32_16x16x32_bf16 v[18:21], v[156:159], v[210:213], v[18:21]
	v_mfma_f32_16x16x32_bf16 v[10:13], v[174:177], v[210:213], v[10:13]
	v_mfma_f32_16x16x32_bf16 v[6:9], v[156:159], v[218:221], v[6:9]
	v_mfma_f32_16x16x32_bf16 v[2:5], v[174:177], v[218:221], v[2:5]
	v_mfma_f32_16x16x32_bf16 v[50:53], v[170:173], v[186:189], v[50:53]
	v_mfma_f32_16x16x32_bf16 v[42:45], v[178:181], v[186:189], v[42:45]
	v_mfma_f32_16x16x32_bf16 v[34:37], v[170:173], v[204:207], v[34:37]
	v_mfma_f32_16x16x32_bf16 v[26:29], v[178:181], v[204:207], v[26:29]
	v_mfma_f32_16x16x32_bf16 v[18:21], v[170:173], v[214:217], v[18:21]
	v_mfma_f32_16x16x32_bf16 v[10:13], v[178:181], v[214:217], v[10:13]
	v_mfma_f32_16x16x32_bf16 v[6:9], v[170:173], v[222:225], v[6:9]
	v_mfma_f32_16x16x32_bf16 v[2:5], v[178:181], v[222:225], v[2:5]
	s_barrier
	s_setprio 0
	s_add_i32 s46, s46, 2
	s_add_u32 s44, s44, 0x100
	s_addc_u32 s45, s45, 0
	s_add_u32 s60, s60, 0x100
	s_addc_u32 s61, s61, 0
	s_cmp_gt_u32 s46, 13
	s_cbranch_scc0 .LBB0_559
	s_and_b64 vcc, exec, s[4:5]
	s_cbranch_vccz .LBB0_562
	s_barrier

; #define PG8_STAGE(bufoff, gbase, voff) do { _Pragma("unroll") for (int _i = 0; _i < 2; ++_i) \
;         __builtin_amdgcn_global_load_lds((const gunsigned*)((const gchar*)(gbase) + (voff)[_i]), (LAS unsigned*)(lds + (bufoff) + ldsw + _i * 8192), 16, 0, 0); } while (0)
; #define PG8_LDA(dst, b, h) do { _Pragma("unroll") for (int m = 0; m < 4; ++m) _Pragma("unroll") for (int k = 0; k < 2; ++k) dst[m][k] = *(const LAS bf16x8*)(lds + PG8_SA(b, h) + aoff + m * 2048 + k * 1024); } while (0)
; #define PG8_LDB(dst, b, h) do { _Pragma("unroll") for (int n = 0; n < 2; ++n) _Pragma("unroll") for (int k = 0; k < 2; ++k) dst[n][k] = *(const LAS bf16x8*)(lds + PG8_SB(b, h) + boff + n * 2048 + k * 1024); } while (0)
; #define PG8_MMA(ai, bj, At, Bt) do { __builtin_amdgcn_s_setprio(1); _Pragma("unroll") for (int m = 0; m < 4; ++m) _Pragma("unroll") for (int n = 0; n < 2; ++n) _Pragma("unroll") for (int k = 0; k < 2; ++k) \
;         acc[ai][bj][m][n] = __builtin_amdgcn_mfma_f32_16x16x32_bf16(Bt[n][k], At[m][k], acc[ai][bj][m][n], 0, 0, 0); __builtin_amdgcn_s_setprio(0); } while (0)
; #define PG8_WAIT_V(n) asm volatile("s_waitcnt vmcnt(" #n ")" ::: "memory")
; #define PG8_WAIT_L(n) asm volatile("s_waitcnt lgkmcnt(" #n ")" ::: "memory")
; #define PG8_BAR __builtin_amdgcn_s_barrier()
; #define PG8_SCHED __builtin_amdgcn_sched_barrier(0)
; template <class Epi, class Sched>
; __device__ __forceinline__ void gemm_phase(LAS unsigned char* lds, const int tid, const Gemm g, const Sched& S, const Epi& E) {
;     ...
;         for (int t = 0; t < nt; t += 2) {
;             const bool last = (t == nt - 2);
;             const gchar* a1 = cA + (size_t)(t + 1) * kstep;
;             const gchar* a2 = last ? nA : cA + (size_t)(t + 2) * kstep; const gchar* b2 = last ? nB : cB + (size_t)(t + 2) * kstep;
;             const gchar* a3 = a2 + kstep; const gchar* b3 = b2 + kstep;
;             PG8_LDB(B0, 0, 0); PG8_LDB(B1, 0, 1); PG8_SCHED; PG8_LDA(At, 0, 0); PG8_STAGE(PG8_SA(1, 1), a1 + hstep, voffA);
;             PG8_WAIT_V(8); PG8_WAIT_L(0); PG8_BAR; PG8_MMA(0, 0, At, B0); PG8_MMA(0, 1, At, B1); PG8_BAR; PG8_SCHED;
;             PG8_LDA(At, 0, 1); PG8_STAGE(PG8_SB(0, 0), b2, voffB); PG8_STAGE(PG8_SB(0, 1), b2 + hstep, voffB); PG8_STAGE(PG8_SA(0, 0), a2, voffA);
;             PG8_WAIT_V(8); PG8_WAIT_L(0); PG8_BAR; PG8_MMA(1, 0, At, B0); PG8_MMA(1, 1, At, B1); PG8_BAR; PG8_SCHED;
.LBB0_598:
	s_add_u32 s20, s62, 0x100
	s_addc_u32 s21, s63, 0
	s_add_i32 s29, 0, 0x10000
	s_cmp_eq_u32 s45, 40
	s_cselect_b32 s73, s9, s21
	s_cselect_b32 s72, s8, s20
	s_cselect_b32 s67, s61, s44
	s_cselect_b32 s66, s60, s31
	s_add_i32 s48, 0, 0x14000
	s_add_i32 m0, s34, 0xc000
	global_load_lds_dwordx4 v186, s[62:63]
	s_add_i32 m0, s34, 0xe000
	s_nop 0
	global_load_lds_dwordx4 v184, s[62:63]
	v_add_u32_e32 v142, s29, v210
	v_add_u32_e32 v158, s48, v210
	ds_read_b128 v[130:133], v142
	ds_read_b128 v[134:137], v142 offset:1024
	ds_read_b128 v[138:141], v142 offset:2048
	ds_read_b128 v[142:145], v142 offset:3072
	ds_read_b128 v[146:149], v158
	ds_read_b128 v[150:153], v158 offset:1024
	ds_read_b128 v[154:157], v158 offset:2048
	ds_read_b128 v[158:161], v158 offset:3072
	ds_read_b128 v[162:165], v214
	ds_read_b128 v[166:169], v214 offset:1024
	ds_read_b128 v[170:173], v214 offset:2048
	ds_read_b128 v[174:177], v214 offset:3072
	ds_read_b128 v[188:191], v214 offset:4096
	ds_read_b128 v[192:195], v214 offset:5120
	ds_read_b128 v[204:207], v214 offset:6144
	ds_read_b128 v[216:219], v214 offset:7168
	s_waitcnt vmcnt(8) lgkmcnt(0)
	s_setprio 1
	s_barrier
	v_mfma_f32_16x16x32_bf16 v[126:129], v[130:133], v[162:165], v[126:129]
	v_mfma_f32_16x16x32_bf16 v[122:125], v[138:141], v[162:165], v[122:125]
	v_mfma_f32_16x16x32_bf16 v[110:113], v[130:133], v[170:173], v[110:113]
	v_mfma_f32_16x16x32_bf16 v[106:109], v[138:141], v[170:173], v[106:109]
	v_mfma_f32_16x16x32_bf16 v[94:97], v[130:133], v[188:191], v[94:97]
	v_mfma_f32_16x16x32_bf16 v[90:93], v[138:141], v[188:191], v[90:93]
	v_mfma_f32_16x16x32_bf16 v[78:81], v[130:133], v[204:207], v[78:81]
	v_mfma_f32_16x16x32_bf16 v[74:77], v[138:141], v[204:207], v[74:77]
	v_mfma_f32_16x16x32_bf16 v[126:129], v[134:137], v[166:169], v[126:129]
	v_mfma_f32_16x16x32_bf16 v[122:125], v[142:145], v[166:169], v[122:125]
	v_mfma_f32_16x16x32_bf16 v[110:113], v[134:137], v[174:177], v[110:113]
	v_mfma_f32_16x16x32_bf16 v[106:109], v[142:145], v[174:177], v[106:109]
	v_mfma_f32_16x16x32_bf16 v[94:97], v[134:137], v[192:195], v[94:97]
	v_mfma_f32_16x16x32_bf16 v[90:93], v[142:145], v[192:195], v[90:93]
	v_mfma_f32_16x16x32_bf16 v[78:81], v[134:137], v[216:219], v[78:81]
	v_mfma_f32_16x16x32_bf16 v[74:77], v[142:145], v[216:219], v[74:77]
	s_setprio 0
	s_setprio 1
	v_mfma_f32_16x16x32_bf16 v[118:121], v[146:149], v[162:165], v[118:121]
	v_mfma_f32_16x16x32_bf16 v[114:117], v[154:157], v[162:165], v[114:117]
	v_mfma_f32_16x16x32_bf16 v[102:105], v[146:149], v[170:173], v[102:105]
	v_mfma_f32_16x16x32_bf16 v[98:101], v[154:157], v[170:173], v[98:101]
	v_mfma_f32_16x16x32_bf16 v[86:89], v[146:149], v[188:191], v[86:89]
	v_mfma_f32_16x16x32_bf16 v[82:85], v[154:157], v[188:191], v[82:85]
	v_mfma_f32_16x16x32_bf16 v[70:73], v[146:149], v[204:207], v[70:73]
	v_mfma_f32_16x16x32_bf16 v[66:69], v[154:157], v[204:207], v[66:69]
	v_mfma_f32_16x16x32_bf16 v[118:121], v[150:153], v[166:169], v[118:121]
	v_mfma_f32_16x16x32_bf16 v[114:117], v[158:161], v[166:169], v[114:117]
	v_mfma_f32_16x16x32_bf16 v[102:105], v[150:153], v[174:177], v[102:105]
	v_mfma_f32_16x16x32_bf16 v[98:101], v[158:161], v[174:177], v[98:101]
	v_mfma_f32_16x16x32_bf16 v[86:89], v[150:153], v[192:195], v[86:89]
	v_mfma_f32_16x16x32_bf16 v[82:85], v[158:161], v[192:195], v[82:85]
	v_mfma_f32_16x16x32_bf16 v[70:73], v[150:153], v[216:219], v[70:73]
	v_mfma_f32_16x16x32_bf16 v[66:69], v[158:161], v[216:219], v[66:69]
	s_barrier
	s_setprio 0
	s_add_i32 s29, s29, s15
	s_mov_b32 m0, s29
	global_load_lds_dwordx4 v0, s[66:67]
	s_add_i32 m0, s29, 0x2000
	s_add_u32 s46, s66, 0xb0000
	s_addc_u32 s47, s67, 0
	s_add_i32 s29, s48, s15
	global_load_lds_dwordx4 v182, s[66:67]
	s_mov_b32 m0, s29
	s_nop 0
	global_load_lds_dwordx4 v0, s[46:47]
	s_add_i32 m0, s29, 0x2000
	s_nop 0
	global_load_lds_dwordx4 v182, s[46:47]
	s_mov_b32 m0, s34
	s_nop 0
	global_load_lds_dwordx4 v178, s[72:73]
	s_mov_b32 m0, s12
	s_nop 0
	global_load_lds_dwordx4 v180, s[72:73]
	ds_read_b128 v[162:165], v214 offset:16384
	ds_read_b128 v[166:169], v214 offset:17408
	ds_read_b128 v[170:173], v214 offset:18432
	ds_read_b128 v[174:177], v214 offset:19456
	ds_read_b128 v[188:191], v214 offset:20480
	ds_read_b128 v[192:195], v214 offset:21504
	ds_read_b128 v[204:207], v214 offset:22528
	ds_read_b128 v[216:219], v214 offset:23552
	s_waitcnt vmcnt(8) lgkmcnt(0)
	s_setprio 1
	s_barrier
	v_mfma_f32_16x16x32_bf16 v[62:65], v[130:133], v[162:165], v[62:65]
	v_mfma_f32_16x16x32_bf16 v[58:61], v[138:141], v[162:165], v[58:61]
	v_mfma_f32_16x16x32_bf16 v[46:49], v[130:133], v[170:173], v[46:49]
	v_mfma_f32_16x16x32_bf16 v[42:45], v[138:141], v[170:173], v[42:45]
	v_mfma_f32_16x16x32_bf16 v[30:33], v[130:133], v[188:191], v[30:33]
	v_mfma_f32_16x16x32_bf16 v[26:29], v[138:141], v[188:191], v[26:29]
	v_mfma_f32_16x16x32_bf16 v[14:17], v[130:133], v[204:207], v[14:17]
	v_mfma_f32_16x16x32_bf16 v[10:13], v[138:141], v[204:207], v[10:13]
	v_mfma_f32_16x16x32_bf16 v[62:65], v[134:137], v[166:169], v[62:65]
	v_mfma_f32_16x16x32_bf16 v[58:61], v[142:145], v[166:169], v[58:61]
	v_mfma_f32_16x16x32_bf16 v[46:49], v[134:137], v[174:177], v[46:49]
	v_mfma_f32_16x16x32_bf16 v[42:45], v[142:145], v[174:177], v[42:45]
	v_mfma_f32_16x16x32_bf16 v[30:33], v[134:137], v[192:195], v[30:33]
	v_mfma_f32_16x16x32_bf16 v[26:29], v[142:145], v[192:195], v[26:29]
	v_mfma_f32_16x16x32_bf16 v[14:17], v[134:137], v[216:219], v[14:17]
	v_mfma_f32_16x16x32_bf16 v[10:13], v[142:145], v[216:219], v[10:13]
	s_setprio 0
	s_setprio 1
	v_mfma_f32_16x16x32_bf16 v[54:57], v[146:149], v[162:165], v[54:57]
	v_mfma_f32_16x16x32_bf16 v[50:53], v[154:157], v[162:165], v[50:53]
	v_mfma_f32_16x16x32_bf16 v[38:41], v[146:149], v[170:173], v[38:41]
	v_mfma_f32_16x16x32_bf16 v[34:37], v[154:157], v[170:173], v[34:37]
	v_mfma_f32_16x16x32_bf16 v[22:25], v[146:149], v[188:191], v[22:25]
	v_mfma_f32_16x16x32_bf16 v[18:21], v[154:157], v[188:191], v[18:21]
	v_mfma_f32_16x16x32_bf16 v[6:9], v[146:149], v[204:207], v[6:9]
	v_mfma_f32_16x16x32_bf16 v[2:5], v[154:157], v[204:207], v[2:5]
	v_mfma_f32_16x16x32_bf16 v[54:57], v[150:153], v[166:169], v[54:57]
	v_mfma_f32_16x16x32_bf16 v[50:53], v[158:161], v[166:169], v[50:53]
	v_mfma_f32_16x16x32_bf16 v[38:41], v[150:153], v[174:177], v[38:41]
	v_mfma_f32_16x16x32_bf16 v[34:37], v[158:161], v[174:177], v[34:37]
	v_mfma_f32_16x16x32_bf16 v[22:25], v[150:153], v[192:195], v[22:25]
	v_mfma_f32_16x16x32_bf16 v[18:21], v[158:161], v[192:195], v[18:21]
	v_mfma_f32_16x16x32_bf16 v[6:9], v[150:153], v[216:219], v[6:9]
	v_mfma_f32_16x16x32_bf16 v[2:5], v[158:161], v[216:219], v[2:5]
	s_barrier
; #define PG8_STAGE(bufoff, gbase, voff) do { _Pragma("unroll") for (int _i = 0; _i < 2; ++_i) \
;         __builtin_amdgcn_global_load_lds((const gunsigned*)((const gchar*)(gbase) + (voff)[_i]), (LAS unsigned*)(lds + (bufoff) + ldsw + _i * 8192), 16, 0, 0); } while (0)
; #define PG8_LDA(dst, b, h) do { _Pragma("unroll") for (int m = 0; m < 4; ++m) _Pragma("unroll") for (int k = 0; k < 2; ++k) dst[m][k] = *(const LAS bf16x8*)(lds + PG8_SA(b, h) + aoff + m * 2048 + k * 1024); } while (0)
; #define PG8_LDB(dst, b, h) do { _Pragma("unroll") for (int n = 0; n < 2; ++n) _Pragma("unroll") for (int k = 0; k < 2; ++k) dst[n][k] = *(const LAS bf16x8*)(lds + PG8_SB(b, h) + boff + n * 2048 + k * 1024); } while (0)
; #define PG8_MMA(ai, bj, At, Bt) do { __builtin_amdgcn_s_setprio(1); _Pragma("unroll") for (int m = 0; m < 4; ++m) _Pragma("unroll") for (int n = 0; n < 2; ++n) _Pragma("unroll") for (int k = 0; k < 2; ++k) \
;         acc[ai][bj][m][n] = __builtin_amdgcn_mfma_f32_16x16x32_bf16(Bt[n][k], At[m][k], acc[ai][bj][m][n], 0, 0, 0); __builtin_amdgcn_s_setprio(0); } while (0)
; #define PG8_WAIT_V(n) asm volatile("s_waitcnt vmcnt(" #n ")" ::: "memory")
; #define PG8_WAIT_L(n) asm volatile("s_waitcnt lgkmcnt(" #n ")" ::: "memory")
; #define PG8_BAR __builtin_amdgcn_s_barrier()
; #define PG8_SCHED __builtin_amdgcn_sched_barrier(0)
; template <class Epi, class Sched>
; __device__ __forceinline__ void gemm_phase(LAS unsigned char* lds, const int tid, const Gemm g, const Sched& S, const Epi& E) {
;     ...
;             PG8_LDB(B0, 1, 0); PG8_LDB(B1, 1, 1); PG8_SCHED; PG8_LDA(At, 1, 0); PG8_STAGE(PG8_SA(0, 1), a2 + hstep, voffA);
;             PG8_WAIT_V(8); PG8_WAIT_L(0); PG8_BAR; PG8_MMA(0, 0, At, B0); PG8_MMA(0, 1, At, B1); PG8_BAR; PG8_SCHED;
;             PG8_LDA(At, 1, 1); PG8_STAGE(PG8_SB(1, 0), b3, voffB); PG8_STAGE(PG8_SB(1, 1), b3 + hstep, voffB); PG8_STAGE(PG8_SA(1, 0), a3, voffA);
;             PG8_WAIT_V(8); PG8_WAIT_L(0); PG8_BAR; PG8_MMA(1, 0, At, B0); PG8_MMA(1, 1, At, B1); PG8_BAR; PG8_SCHED;
;         }
;         if (wr == 0) PG8_BAR;
	s_setprio 0
	s_add_i32 s29, 0, 0x18000
	s_add_i32 s48, 0, 0x1c000
	s_add_u32 s46, s72, 0xb0000
	s_addc_u32 s47, s73, 0
	s_mov_b32 m0, s35
	global_load_lds_dwordx4 v178, s[46:47]
	s_mov_b32 m0, s36
	s_nop 0
	global_load_lds_dwordx4 v180, s[46:47]
	v_add_u32_e32 v142, s29, v210
	v_add_u32_e32 v158, s48, v210
	ds_read_b128 v[130:133], v142
	ds_read_b128 v[134:137], v142 offset:1024
	ds_read_b128 v[138:141], v142 offset:2048
	ds_read_b128 v[142:145], v142 offset:3072
	ds_read_b128 v[146:149], v158
	ds_read_b128 v[150:153], v158 offset:1024
	ds_read_b128 v[154:157], v158 offset:2048
	ds_read_b128 v[158:161], v158 offset:3072
	ds_read_b128 v[162:165], v214 offset:32768
	ds_read_b128 v[166:169], v214 offset:33792
	ds_read_b128 v[170:173], v214 offset:34816
	ds_read_b128 v[174:177], v214 offset:35840
	ds_read_b128 v[188:191], v214 offset:36864
	ds_read_b128 v[192:195], v214 offset:37888
	ds_read_b128 v[204:207], v214 offset:38912
	ds_read_b128 v[216:219], v214 offset:39936
	s_waitcnt vmcnt(8) lgkmcnt(0)
	s_setprio 1
	s_barrier
	v_mfma_f32_16x16x32_bf16 v[126:129], v[130:133], v[162:165], v[126:129]
	v_mfma_f32_16x16x32_bf16 v[122:125], v[138:141], v[162:165], v[122:125]
	v_mfma_f32_16x16x32_bf16 v[110:113], v[130:133], v[170:173], v[110:113]
	v_mfma_f32_16x16x32_bf16 v[106:109], v[138:141], v[170:173], v[106:109]
	v_mfma_f32_16x16x32_bf16 v[94:97], v[130:133], v[188:191], v[94:97]
	v_mfma_f32_16x16x32_bf16 v[90:93], v[138:141], v[188:191], v[90:93]
	v_mfma_f32_16x16x32_bf16 v[78:81], v[130:133], v[204:207], v[78:81]
	v_mfma_f32_16x16x32_bf16 v[74:77], v[138:141], v[204:207], v[74:77]
	v_mfma_f32_16x16x32_bf16 v[126:129], v[134:137], v[166:169], v[126:129]
	v_mfma_f32_16x16x32_bf16 v[122:125], v[142:145], v[166:169], v[122:125]
	v_mfma_f32_16x16x32_bf16 v[110:113], v[134:137], v[174:177], v[110:113]
	v_mfma_f32_16x16x32_bf16 v[106:109], v[142:145], v[174:177], v[106:109]
	v_mfma_f32_16x16x32_bf16 v[94:97], v[134:137], v[192:195], v[94:97]
	v_mfma_f32_16x16x32_bf16 v[90:93], v[142:145], v[192:195], v[90:93]
	v_mfma_f32_16x16x32_bf16 v[78:81], v[134:137], v[216:219], v[78:81]
	v_mfma_f32_16x16x32_bf16 v[74:77], v[142:145], v[216:219], v[74:77]
	s_setprio 0
	s_setprio 1
	v_mfma_f32_16x16x32_bf16 v[118:121], v[146:149], v[162:165], v[118:121]
	v_mfma_f32_16x16x32_bf16 v[114:117], v[154:157], v[162:165], v[114:117]
	v_mfma_f32_16x16x32_bf16 v[102:105], v[146:149], v[170:173], v[102:105]
	v_mfma_f32_16x16x32_bf16 v[98:101], v[154:157], v[170:173], v[98:101]
	v_mfma_f32_16x16x32_bf16 v[86:89], v[146:149], v[188:191], v[86:89]
	v_mfma_f32_16x16x32_bf16 v[82:85], v[154:157], v[188:191], v[82:85]
	v_mfma_f32_16x16x32_bf16 v[70:73], v[146:149], v[204:207], v[70:73]
	v_mfma_f32_16x16x32_bf16 v[66:69], v[154:157], v[204:207], v[66:69]
	v_mfma_f32_16x16x32_bf16 v[118:121], v[150:153], v[166:169], v[118:121]
	v_mfma_f32_16x16x32_bf16 v[114:117], v[158:161], v[166:169], v[114:117]
	v_mfma_f32_16x16x32_bf16 v[102:105], v[150:153], v[174:177], v[102:105]
	v_mfma_f32_16x16x32_bf16 v[98:101], v[158:161], v[174:177], v[98:101]
	v_mfma_f32_16x16x32_bf16 v[86:89], v[150:153], v[192:195], v[86:89]
	v_mfma_f32_16x16x32_bf16 v[82:85], v[158:161], v[192:195], v[82:85]
	v_mfma_f32_16x16x32_bf16 v[70:73], v[150:153], v[216:219], v[70:73]
	v_mfma_f32_16x16x32_bf16 v[66:69], v[158:161], v[216:219], v[66:69]
	s_barrier
	s_setprio 0
	s_add_i32 s29, s29, s15
	s_mov_b32 m0, s29
	ds_read_b128 v[162:165], v214 offset:49152
	global_load_lds_dwordx4 v221, s[66:67]
	s_add_i32 m0, s29, 0x2000
	s_add_u32 s46, s66, 0xb0080
	s_addc_u32 s47, s67, 0
	s_add_i32 s29, s48, s15
	global_load_lds_dwordx4 v223, s[66:67]
	s_mov_b32 m0, s29
	s_nop 0
	global_load_lds_dwordx4 v0, s[46:47]
	s_add_i32 m0, s29, 0x2000
	s_nop 0
	global_load_lds_dwordx4 v182, s[46:47]
	s_mov_b32 m0, s37
	s_nop 0
	global_load_lds_dwordx4 v225, s[72:73]
	s_mov_b32 m0, s38
	s_nop 0
	global_load_lds_dwordx4 v227, s[72:73]
	ds_read_b128 v[166:169], v214 offset:50176
	ds_read_b128 v[170:173], v214 offset:51200
	ds_read_b128 v[174:177], v214 offset:52224
	ds_read_b128 v[188:191], v214 offset:53248
	ds_read_b128 v[192:195], v214 offset:54272
	ds_read_b128 v[204:207], v214 offset:55296
	ds_read_b128 v[216:219], v214 offset:56320
	s_waitcnt vmcnt(8) lgkmcnt(0)
	s_setprio 1
	s_barrier
	v_mfma_f32_16x16x32_bf16 v[62:65], v[130:133], v[162:165], v[62:65]
	v_mfma_f32_16x16x32_bf16 v[58:61], v[138:141], v[162:165], v[58:61]
	v_mfma_f32_16x16x32_bf16 v[46:49], v[130:133], v[170:173], v[46:49]
	v_mfma_f32_16x16x32_bf16 v[42:45], v[138:141], v[170:173], v[42:45]
	v_mfma_f32_16x16x32_bf16 v[30:33], v[130:133], v[188:191], v[30:33]
	v_mfma_f32_16x16x32_bf16 v[26:29], v[138:141], v[188:191], v[26:29]
	v_mfma_f32_16x16x32_bf16 v[14:17], v[130:133], v[204:207], v[14:17]
	v_mfma_f32_16x16x32_bf16 v[10:13], v[138:141], v[204:207], v[10:13]
	v_mfma_f32_16x16x32_bf16 v[62:65], v[134:137], v[166:169], v[62:65]
	v_mfma_f32_16x16x32_bf16 v[58:61], v[142:145], v[166:169], v[58:61]
	v_mfma_f32_16x16x32_bf16 v[46:49], v[134:137], v[174:177], v[46:49]
	v_mfma_f32_16x16x32_bf16 v[42:45], v[142:145], v[174:177], v[42:45]
	v_mfma_f32_16x16x32_bf16 v[30:33], v[134:137], v[192:195], v[30:33]
	v_mfma_f32_16x16x32_bf16 v[26:29], v[142:145], v[192:195], v[26:29]
	v_mfma_f32_16x16x32_bf16 v[14:17], v[134:137], v[216:219], v[14:17]
	v_mfma_f32_16x16x32_bf16 v[10:13], v[142:145], v[216:219], v[10:13]
	s_setprio 0
	s_setprio 1
	v_mfma_f32_16x16x32_bf16 v[54:57], v[146:149], v[162:165], v[54:57]
	v_mfma_f32_16x16x32_bf16 v[50:53], v[154:157], v[162:165], v[50:53]
	v_mfma_f32_16x16x32_bf16 v[38:41], v[146:149], v[170:173], v[38:41]
	v_mfma_f32_16x16x32_bf16 v[34:37], v[154:157], v[170:173], v[34:37]
	v_mfma_f32_16x16x32_bf16 v[22:25], v[146:149], v[188:191], v[22:25]
	v_mfma_f32_16x16x32_bf16 v[18:21], v[154:157], v[188:191], v[18:21]
	v_mfma_f32_16x16x32_bf16 v[6:9], v[146:149], v[204:207], v[6:9]
	v_mfma_f32_16x16x32_bf16 v[2:5], v[154:157], v[204:207], v[2:5]
	v_mfma_f32_16x16x32_bf16 v[54:57], v[150:153], v[166:169], v[54:57]
	v_mfma_f32_16x16x32_bf16 v[50:53], v[158:161], v[166:169], v[50:53]
	v_mfma_f32_16x16x32_bf16 v[38:41], v[150:153], v[174:177], v[38:41]
	v_mfma_f32_16x16x32_bf16 v[34:37], v[158:161], v[174:177], v[34:37]
	v_mfma_f32_16x16x32_bf16 v[22:25], v[150:153], v[192:195], v[22:25]
	v_mfma_f32_16x16x32_bf16 v[18:21], v[158:161], v[192:195], v[18:21]
	v_mfma_f32_16x16x32_bf16 v[6:9], v[150:153], v[216:219], v[6:9]
	v_mfma_f32_16x16x32_bf16 v[2:5], v[158:161], v[216:219], v[2:5]
	s_barrier
	s_setprio 0
	s_add_i32 s45, s45, 2
	s_add_u32 s31, s31, 0x100
	s_addc_u32 s44, s44, 0
	s_cmp_gt_u32 s45, 41
	s_mov_b64 s[62:63], s[20:21]
	s_cbranch_scc0 .LBB0_598
	s_and_b64 vcc, exec, s[58:59]
	s_cbranch_vccz .LBB0_601
	s_barrier

; #define PG8_STAGE(bufoff, gbase, voff) do { _Pragma("unroll") for (int _i = 0; _i < 2; ++_i) \
;         __builtin_amdgcn_global_load_lds((const gunsigned*)((const gchar*)(gbase) + (voff)[_i]), (LAS unsigned*)(lds + (bufoff) + ldsw + _i * 8192), 16, 0, 0); } while (0)
; #define PG8_LDA(dst, b, h) do { _Pragma("unroll") for (int m = 0; m < 4; ++m) _Pragma("unroll") for (int k = 0; k < 2; ++k) dst[m][k] = *(const LAS bf16x8*)(lds + PG8_SA(b, h) + aoff + m * 2048 + k * 1024); } while (0)
; #define PG8_LDB(dst, b, h) do { _Pragma("unroll") for (int n = 0; n < 2; ++n) _Pragma("unroll") for (int k = 0; k < 2; ++k) dst[n][k] = *(const LAS bf16x8*)(lds + PG8_SB(b, h) + boff + n * 2048 + k * 1024); } while (0)
; #define PG8_MMA(ai, bj, At, Bt) do { __builtin_amdgcn_s_setprio(1); _Pragma("unroll") for (int m = 0; m < 4; ++m) _Pragma("unroll") for (int n = 0; n < 2; ++n) _Pragma("unroll") for (int k = 0; k < 2; ++k) \
;         acc[ai][bj][m][n] = __builtin_amdgcn_mfma_f32_16x16x32_bf16(Bt[n][k], At[m][k], acc[ai][bj][m][n], 0, 0, 0); __builtin_amdgcn_s_setprio(0); } while (0)
; #define PG8_WAIT_V(n) asm volatile("s_waitcnt vmcnt(" #n ")" ::: "memory")
; #define PG8_WAIT_L(n) asm volatile("s_waitcnt lgkmcnt(" #n ")" ::: "memory")
; #define PG8_BAR __builtin_amdgcn_s_barrier()
; #define PG8_SCHED __builtin_amdgcn_sched_barrier(0)
; template <class Epi, class Sched>
; __device__ __forceinline__ void gemm_phase(LAS unsigned char* lds, const int tid, const Gemm g, const Sched& S, const Epi& E) {
;     ...
;         for (int t = 0; t < nt; t += 2) {
;             const bool last = (t == nt - 2);
;             const gchar* a1 = cA + (size_t)(t + 1) * kstep;
;             const gchar* a2 = last ? nA : cA + (size_t)(t + 2) * kstep; const gchar* b2 = last ? nB : cB + (size_t)(t + 2) * kstep;
;             const gchar* a3 = a2 + kstep; const gchar* b3 = b2 + kstep;
;             PG8_LDB(B0, 0, 0); PG8_LDB(B1, 0, 1); PG8_SCHED; PG8_LDA(At, 0, 0); PG8_STAGE(PG8_SA(1, 1), a1 + hstep, voffA);
;             PG8_WAIT_V(8); PG8_WAIT_L(0); PG8_BAR; PG8_MMA(0, 0, At, B0); PG8_MMA(0, 1, At, B1); PG8_BAR; PG8_SCHED;
;             PG8_LDA(At, 0, 1); PG8_STAGE(PG8_SB(0, 0), b2, voffB); PG8_STAGE(PG8_SB(0, 1), b2 + hstep, voffB); PG8_STAGE(PG8_SA(0, 0), a2, voffA);
;             PG8_WAIT_V(8); PG8_WAIT_L(0); PG8_BAR; PG8_MMA(1, 0, At, B0); PG8_MMA(1, 1, At, B1); PG8_BAR; PG8_SCHED;
.LBB0_647:
	s_add_u32 s20, s58, 0xfffc0080
	s_addc_u32 s21, s59, -1
	s_add_i32 s42, 0, 0x10000
	s_cmp_eq_u32 s41, 12
	s_cselect_b32 s61, s9, s21
	s_cselect_b32 s60, s37, s20
	s_cselect_b32 s21, s7, s40
	s_cselect_b32 s20, s38, s39
	s_add_i32 s44, 0, 0x14000
	s_add_i32 m0, s23, 0xc000
	global_load_lds_dwordx4 v138, s[58:59]
	s_add_i32 m0, s23, 0xe000
	s_nop 0
	global_load_lds_dwordx4 v136, s[58:59]
	v_add_u32_e32 v140, s42, v143
	ds_read_b128 v[146:149], v140
	ds_read_b128 v[150:153], v140 offset:1024
	ds_read_b128 v[154:157], v140 offset:2048
	ds_read_b128 v[158:161], v140 offset:3072
	v_add_u32_e32 v140, s44, v143
	ds_read_b128 v[162:165], v140
	ds_read_b128 v[166:169], v140 offset:1024
	ds_read_b128 v[170:173], v140 offset:2048
	ds_read_b128 v[174:177], v140 offset:3072
	ds_read_b128 v[178:181], v145
	ds_read_b128 v[182:185], v145 offset:1024
	ds_read_b128 v[186:189], v145 offset:2048
	ds_read_b128 v[190:193], v145 offset:3072
	ds_read_b128 v[204:207], v145 offset:4096
	ds_read_b128 v[208:211], v145 offset:5120
	ds_read_b128 v[212:215], v145 offset:6144
	ds_read_b128 v[216:219], v145 offset:7168
	s_waitcnt vmcnt(8) lgkmcnt(0)
	s_setprio 1
	s_barrier
	v_mfma_f32_16x16x32_bf16 v[126:129], v[146:149], v[178:181], v[126:129]
	v_mfma_f32_16x16x32_bf16 v[122:125], v[154:157], v[178:181], v[122:125]
	v_mfma_f32_16x16x32_bf16 v[110:113], v[146:149], v[186:189], v[110:113]
	v_mfma_f32_16x16x32_bf16 v[106:109], v[154:157], v[186:189], v[106:109]
	v_mfma_f32_16x16x32_bf16 v[94:97], v[146:149], v[204:207], v[94:97]
	v_mfma_f32_16x16x32_bf16 v[90:93], v[154:157], v[204:207], v[90:93]
	v_mfma_f32_16x16x32_bf16 v[78:81], v[146:149], v[212:215], v[78:81]
	v_mfma_f32_16x16x32_bf16 v[74:77], v[154:157], v[212:215], v[74:77]
	v_mfma_f32_16x16x32_bf16 v[126:129], v[150:153], v[182:185], v[126:129]
	v_mfma_f32_16x16x32_bf16 v[122:125], v[158:161], v[182:185], v[122:125]
	v_mfma_f32_16x16x32_bf16 v[110:113], v[150:153], v[190:193], v[110:113]
	v_mfma_f32_16x16x32_bf16 v[106:109], v[158:161], v[190:193], v[106:109]
	v_mfma_f32_16x16x32_bf16 v[94:97], v[150:153], v[208:211], v[94:97]
	v_mfma_f32_16x16x32_bf16 v[90:93], v[158:161], v[208:211], v[90:93]
	v_mfma_f32_16x16x32_bf16 v[78:81], v[150:153], v[216:219], v[78:81]
	v_mfma_f32_16x16x32_bf16 v[74:77], v[158:161], v[216:219], v[74:77]
	s_setprio 0
	s_setprio 1
	v_mfma_f32_16x16x32_bf16 v[118:121], v[162:165], v[178:181], v[118:121]
	v_mfma_f32_16x16x32_bf16 v[114:117], v[170:173], v[178:181], v[114:117]
	v_mfma_f32_16x16x32_bf16 v[102:105], v[162:165], v[186:189], v[102:105]
	v_mfma_f32_16x16x32_bf16 v[98:101], v[170:173], v[186:189], v[98:101]
	v_mfma_f32_16x16x32_bf16 v[86:89], v[162:165], v[204:207], v[86:89]
	v_mfma_f32_16x16x32_bf16 v[82:85], v[170:173], v[204:207], v[82:85]
	v_mfma_f32_16x16x32_bf16 v[70:73], v[162:165], v[212:215], v[70:73]
	v_mfma_f32_16x16x32_bf16 v[66:69], v[170:173], v[212:215], v[66:69]
	v_mfma_f32_16x16x32_bf16 v[118:121], v[166:169], v[182:185], v[118:121]
	v_mfma_f32_16x16x32_bf16 v[114:117], v[174:177], v[182:185], v[114:117]
	v_mfma_f32_16x16x32_bf16 v[102:105], v[166:169], v[190:193], v[102:105]
	v_mfma_f32_16x16x32_bf16 v[98:101], v[174:177], v[190:193], v[98:101]
	v_mfma_f32_16x16x32_bf16 v[86:89], v[166:169], v[208:211], v[86:89]
	v_mfma_f32_16x16x32_bf16 v[82:85], v[174:177], v[208:211], v[82:85]
	v_mfma_f32_16x16x32_bf16 v[70:73], v[166:169], v[216:219], v[70:73]
	v_mfma_f32_16x16x32_bf16 v[66:69], v[174:177], v[216:219], v[66:69]
	s_barrier
	s_setprio 0
	s_add_i32 s42, s42, s12
	s_mov_b32 m0, s42
	global_load_lds_dwordx4 v0, s[20:21]
	s_add_i32 m0, s42, 0x2000
	s_add_u32 s42, s20, 0x40000
	s_addc_u32 s43, s21, 0
	s_add_i32 s44, s44, s12
	global_load_lds_dwordx4 v130, s[20:21]
	s_mov_b32 m0, s44
	s_nop 0
	global_load_lds_dwordx4 v0, s[42:43]
	s_add_i32 m0, s44, 0x2000
	s_nop 0
	global_load_lds_dwordx4 v130, s[42:43]
	s_mov_b32 m0, s23
	s_nop 0
	global_load_lds_dwordx4 v134, s[60:61]
	s_mov_b32 m0, s24
	s_nop 0
	global_load_lds_dwordx4 v132, s[60:61]
	ds_read_b128 v[178:181], v145 offset:16384
	ds_read_b128 v[182:185], v145 offset:17408
	ds_read_b128 v[186:189], v145 offset:18432
	ds_read_b128 v[190:193], v145 offset:19456
	ds_read_b128 v[204:207], v145 offset:20480
	ds_read_b128 v[208:211], v145 offset:21504
	ds_read_b128 v[212:215], v145 offset:22528
	ds_read_b128 v[216:219], v145 offset:23552
	s_waitcnt vmcnt(8) lgkmcnt(0)
	s_setprio 1
	s_barrier
	v_mfma_f32_16x16x32_bf16 v[62:65], v[146:149], v[178:181], v[62:65]
	v_mfma_f32_16x16x32_bf16 v[58:61], v[154:157], v[178:181], v[58:61]
	v_mfma_f32_16x16x32_bf16 v[46:49], v[146:149], v[186:189], v[46:49]
	v_mfma_f32_16x16x32_bf16 v[42:45], v[154:157], v[186:189], v[42:45]
	v_mfma_f32_16x16x32_bf16 v[30:33], v[146:149], v[204:207], v[30:33]
	v_mfma_f32_16x16x32_bf16 v[26:29], v[154:157], v[204:207], v[26:29]
	v_mfma_f32_16x16x32_bf16 v[14:17], v[146:149], v[212:215], v[14:17]
	v_mfma_f32_16x16x32_bf16 v[10:13], v[154:157], v[212:215], v[10:13]
	v_mfma_f32_16x16x32_bf16 v[62:65], v[150:153], v[182:185], v[62:65]
	v_mfma_f32_16x16x32_bf16 v[58:61], v[158:161], v[182:185], v[58:61]
	v_mfma_f32_16x16x32_bf16 v[46:49], v[150:153], v[190:193], v[46:49]
	v_mfma_f32_16x16x32_bf16 v[42:45], v[158:161], v[190:193], v[42:45]
	v_mfma_f32_16x16x32_bf16 v[30:33], v[150:153], v[208:211], v[30:33]
	v_mfma_f32_16x16x32_bf16 v[26:29], v[158:161], v[208:211], v[26:29]
	v_mfma_f32_16x16x32_bf16 v[14:17], v[150:153], v[216:219], v[14:17]
	v_mfma_f32_16x16x32_bf16 v[10:13], v[158:161], v[216:219], v[10:13]
	s_setprio 0
	s_setprio 1
	v_mfma_f32_16x16x32_bf16 v[54:57], v[162:165], v[178:181], v[54:57]
	v_mfma_f32_16x16x32_bf16 v[50:53], v[170:173], v[178:181], v[50:53]
	v_mfma_f32_16x16x32_bf16 v[38:41], v[162:165], v[186:189], v[38:41]
	v_mfma_f32_16x16x32_bf16 v[34:37], v[170:173], v[186:189], v[34:37]
	v_mfma_f32_16x16x32_bf16 v[22:25], v[162:165], v[204:207], v[22:25]
	v_mfma_f32_16x16x32_bf16 v[18:21], v[170:173], v[204:207], v[18:21]
	v_mfma_f32_16x16x32_bf16 v[6:9], v[162:165], v[212:215], v[6:9]
	v_mfma_f32_16x16x32_bf16 v[2:5], v[170:173], v[212:215], v[2:5]
	v_mfma_f32_16x16x32_bf16 v[54:57], v[166:169], v[182:185], v[54:57]
	v_mfma_f32_16x16x32_bf16 v[50:53], v[174:177], v[182:185], v[50:53]
	v_mfma_f32_16x16x32_bf16 v[38:41], v[166:169], v[190:193], v[38:41]
	v_mfma_f32_16x16x32_bf16 v[34:37], v[174:177], v[190:193], v[34:37]
	v_mfma_f32_16x16x32_bf16 v[22:25], v[166:169], v[208:211], v[22:25]
	v_mfma_f32_16x16x32_bf16 v[18:21], v[174:177], v[208:211], v[18:21]
	v_mfma_f32_16x16x32_bf16 v[6:9], v[166:169], v[216:219], v[6:9]
	v_mfma_f32_16x16x32_bf16 v[2:5], v[174:177], v[216:219], v[2:5]
	s_barrier
; #define PG8_STAGE(bufoff, gbase, voff) do { _Pragma("unroll") for (int _i = 0; _i < 2; ++_i) \
;         __builtin_amdgcn_global_load_lds((const gunsigned*)((const gchar*)(gbase) + (voff)[_i]), (LAS unsigned*)(lds + (bufoff) + ldsw + _i * 8192), 16, 0, 0); } while (0)
; #define PG8_LDA(dst, b, h) do { _Pragma("unroll") for (int m = 0; m < 4; ++m) _Pragma("unroll") for (int k = 0; k < 2; ++k) dst[m][k] = *(const LAS bf16x8*)(lds + PG8_SA(b, h) + aoff + m * 2048 + k * 1024); } while (0)
; #define PG8_LDB(dst, b, h) do { _Pragma("unroll") for (int n = 0; n < 2; ++n) _Pragma("unroll") for (int k = 0; k < 2; ++k) dst[n][k] = *(const LAS bf16x8*)(lds + PG8_SB(b, h) + boff + n * 2048 + k * 1024); } while (0)
; #define PG8_MMA(ai, bj, At, Bt) do { __builtin_amdgcn_s_setprio(1); _Pragma("unroll") for (int m = 0; m < 4; ++m) _Pragma("unroll") for (int n = 0; n < 2; ++n) _Pragma("unroll") for (int k = 0; k < 2; ++k) \
;         acc[ai][bj][m][n] = __builtin_amdgcn_mfma_f32_16x16x32_bf16(Bt[n][k], At[m][k], acc[ai][bj][m][n], 0, 0, 0); __builtin_amdgcn_s_setprio(0); } while (0)
; #define PG8_WAIT_V(n) asm volatile("s_waitcnt vmcnt(" #n ")" ::: "memory")
; #define PG8_WAIT_L(n) asm volatile("s_waitcnt lgkmcnt(" #n ")" ::: "memory")
; #define PG8_BAR __builtin_amdgcn_s_barrier()
; #define PG8_SCHED __builtin_amdgcn_sched_barrier(0)
; template <class Epi, class Sched>
; __device__ __forceinline__ void gemm_phase(LAS unsigned char* lds, const int tid, const Gemm g, const Sched& S, const Epi& E) {
;     ...
;             PG8_LDB(B0, 1, 0); PG8_LDB(B1, 1, 1); PG8_SCHED; PG8_LDA(At, 1, 0); PG8_STAGE(PG8_SA(0, 1), a2 + hstep, voffA);
;             PG8_WAIT_V(8); PG8_WAIT_L(0); PG8_BAR; PG8_MMA(0, 0, At, B0); PG8_MMA(0, 1, At, B1); PG8_BAR; PG8_SCHED;
;             PG8_LDA(At, 1, 1); PG8_STAGE(PG8_SB(1, 0), b3, voffB); PG8_STAGE(PG8_SB(1, 1), b3 + hstep, voffB); PG8_STAGE(PG8_SA(1, 0), a3, voffA);
;             PG8_WAIT_V(8); PG8_WAIT_L(0); PG8_BAR; PG8_MMA(1, 0, At, B0); PG8_MMA(1, 1, At, B1); PG8_BAR; PG8_SCHED;
;         }
;         if (wr == 0) PG8_BAR;
	s_setprio 0
	s_add_i32 s44, 0, 0x18000
	s_add_i32 s45, 0, 0x1c000
	s_add_u32 s42, s60, 0x40000
	s_addc_u32 s43, s61, 0
	s_mov_b32 m0, s29
	global_load_lds_dwordx4 v134, s[42:43]
	s_mov_b32 m0, s30
	s_nop 0
	global_load_lds_dwordx4 v132, s[42:43]
	v_add_u32_e32 v158, s44, v143
	v_add_u32_e32 v174, s45, v143
	ds_read_b128 v[146:149], v158
	ds_read_b128 v[150:153], v158 offset:1024
	ds_read_b128 v[154:157], v158 offset:2048
	ds_read_b128 v[158:161], v158 offset:3072
	ds_read_b128 v[162:165], v174
	ds_read_b128 v[166:169], v174 offset:1024
	ds_read_b128 v[170:173], v174 offset:2048
	ds_read_b128 v[174:177], v174 offset:3072
	ds_read_b128 v[178:181], v145 offset:32768
	ds_read_b128 v[182:185], v145 offset:33792
	ds_read_b128 v[186:189], v145 offset:34816
	ds_read_b128 v[190:193], v145 offset:35840
	ds_read_b128 v[204:207], v145 offset:36864
	ds_read_b128 v[208:211], v145 offset:37888
	ds_read_b128 v[212:215], v145 offset:38912
	ds_read_b128 v[216:219], v145 offset:39936
	s_waitcnt vmcnt(8) lgkmcnt(0)
	s_setprio 1
	s_barrier
	v_mfma_f32_16x16x32_bf16 v[126:129], v[146:149], v[178:181], v[126:129]
	v_mfma_f32_16x16x32_bf16 v[122:125], v[154:157], v[178:181], v[122:125]
	v_mfma_f32_16x16x32_bf16 v[110:113], v[146:149], v[186:189], v[110:113]
	v_mfma_f32_16x16x32_bf16 v[106:109], v[154:157], v[186:189], v[106:109]
	v_mfma_f32_16x16x32_bf16 v[94:97], v[146:149], v[204:207], v[94:97]
	v_mfma_f32_16x16x32_bf16 v[90:93], v[154:157], v[204:207], v[90:93]
	v_mfma_f32_16x16x32_bf16 v[78:81], v[146:149], v[212:215], v[78:81]
	v_mfma_f32_16x16x32_bf16 v[74:77], v[154:157], v[212:215], v[74:77]
	v_mfma_f32_16x16x32_bf16 v[126:129], v[150:153], v[182:185], v[126:129]
	v_mfma_f32_16x16x32_bf16 v[122:125], v[158:161], v[182:185], v[122:125]
	v_mfma_f32_16x16x32_bf16 v[110:113], v[150:153], v[190:193], v[110:113]
	v_mfma_f32_16x16x32_bf16 v[106:109], v[158:161], v[190:193], v[106:109]
	v_mfma_f32_16x16x32_bf16 v[94:97], v[150:153], v[208:211], v[94:97]
	v_mfma_f32_16x16x32_bf16 v[90:93], v[158:161], v[208:211], v[90:93]
	v_mfma_f32_16x16x32_bf16 v[78:81], v[150:153], v[216:219], v[78:81]
	v_mfma_f32_16x16x32_bf16 v[74:77], v[158:161], v[216:219], v[74:77]
	s_setprio 0
	s_setprio 1
	v_mfma_f32_16x16x32_bf16 v[118:121], v[162:165], v[178:181], v[118:121]
	v_mfma_f32_16x16x32_bf16 v[114:117], v[170:173], v[178:181], v[114:117]
	v_mfma_f32_16x16x32_bf16 v[102:105], v[162:165], v[186:189], v[102:105]
	v_mfma_f32_16x16x32_bf16 v[98:101], v[170:173], v[186:189], v[98:101]
	v_mfma_f32_16x16x32_bf16 v[86:89], v[162:165], v[204:207], v[86:89]
	v_mfma_f32_16x16x32_bf16 v[82:85], v[170:173], v[204:207], v[82:85]
	v_mfma_f32_16x16x32_bf16 v[70:73], v[162:165], v[212:215], v[70:73]
	v_mfma_f32_16x16x32_bf16 v[66:69], v[170:173], v[212:215], v[66:69]
	v_mfma_f32_16x16x32_bf16 v[118:121], v[166:169], v[182:185], v[118:121]
	v_mfma_f32_16x16x32_bf16 v[114:117], v[174:177], v[182:185], v[114:117]
	v_mfma_f32_16x16x32_bf16 v[102:105], v[166:169], v[190:193], v[102:105]
	v_mfma_f32_16x16x32_bf16 v[98:101], v[174:177], v[190:193], v[98:101]
	v_mfma_f32_16x16x32_bf16 v[86:89], v[166:169], v[208:211], v[86:89]
	v_mfma_f32_16x16x32_bf16 v[82:85], v[174:177], v[208:211], v[82:85]
	v_mfma_f32_16x16x32_bf16 v[70:73], v[166:169], v[216:219], v[70:73]
	v_mfma_f32_16x16x32_bf16 v[66:69], v[174:177], v[216:219], v[66:69]
	s_barrier
	s_setprio 0
	s_add_i32 s42, s44, s12
	s_mov_b32 m0, s42
	ds_read_b128 v[178:181], v145 offset:49152
	global_load_lds_dwordx4 v141, s[20:21]
	s_add_i32 m0, s42, 0x2000
	s_add_i32 s42, s45, s12
	global_load_lds_dwordx4 v195, s[20:21]
	s_add_u32 s20, s20, 0x40080
	s_addc_u32 s21, s21, 0
	s_mov_b32 m0, s42
	s_nop 0
	global_load_lds_dwordx4 v0, s[20:21]
	s_add_i32 m0, s42, 0x2000
	s_nop 0
	global_load_lds_dwordx4 v130, s[20:21]
	s_mov_b32 m0, s31
	s_nop 0
	global_load_lds_dwordx4 v221, s[60:61]
	s_mov_b32 m0, s34
	s_nop 0
	global_load_lds_dwordx4 v223, s[60:61]
	ds_read_b128 v[182:185], v145 offset:50176
	ds_read_b128 v[186:189], v145 offset:51200
	ds_read_b128 v[190:193], v145 offset:52224
	ds_read_b128 v[204:207], v145 offset:53248
	ds_read_b128 v[208:211], v145 offset:54272
	ds_read_b128 v[212:215], v145 offset:55296
	ds_read_b128 v[216:219], v145 offset:56320
	s_waitcnt vmcnt(8) lgkmcnt(0)
	s_setprio 1
	s_barrier
	v_mfma_f32_16x16x32_bf16 v[62:65], v[146:149], v[178:181], v[62:65]
	v_mfma_f32_16x16x32_bf16 v[58:61], v[154:157], v[178:181], v[58:61]
	v_mfma_f32_16x16x32_bf16 v[46:49], v[146:149], v[186:189], v[46:49]
	v_mfma_f32_16x16x32_bf16 v[42:45], v[154:157], v[186:189], v[42:45]
	v_mfma_f32_16x16x32_bf16 v[30:33], v[146:149], v[204:207], v[30:33]
	v_mfma_f32_16x16x32_bf16 v[26:29], v[154:157], v[204:207], v[26:29]
	v_mfma_f32_16x16x32_bf16 v[14:17], v[146:149], v[212:215], v[14:17]
	v_mfma_f32_16x16x32_bf16 v[10:13], v[154:157], v[212:215], v[10:13]
	v_mfma_f32_16x16x32_bf16 v[62:65], v[150:153], v[182:185], v[62:65]
	v_mfma_f32_16x16x32_bf16 v[58:61], v[158:161], v[182:185], v[58:61]
	v_mfma_f32_16x16x32_bf16 v[46:49], v[150:153], v[190:193], v[46:49]
	v_mfma_f32_16x16x32_bf16 v[42:45], v[158:161], v[190:193], v[42:45]
	v_mfma_f32_16x16x32_bf16 v[30:33], v[150:153], v[208:211], v[30:33]
	v_mfma_f32_16x16x32_bf16 v[26:29], v[158:161], v[208:211], v[26:29]
	v_mfma_f32_16x16x32_bf16 v[14:17], v[150:153], v[216:219], v[14:17]
	v_mfma_f32_16x16x32_bf16 v[10:13], v[158:161], v[216:219], v[10:13]
	s_setprio 0
	s_setprio 1
	v_mfma_f32_16x16x32_bf16 v[54:57], v[162:165], v[178:181], v[54:57]
	v_mfma_f32_16x16x32_bf16 v[50:53], v[170:173], v[178:181], v[50:53]
	v_mfma_f32_16x16x32_bf16 v[38:41], v[162:165], v[186:189], v[38:41]
	v_mfma_f32_16x16x32_bf16 v[34:37], v[170:173], v[186:189], v[34:37]
	v_mfma_f32_16x16x32_bf16 v[22:25], v[162:165], v[204:207], v[22:25]
	v_mfma_f32_16x16x32_bf16 v[18:21], v[170:173], v[204:207], v[18:21]
	v_mfma_f32_16x16x32_bf16 v[6:9], v[162:165], v[212:215], v[6:9]
	v_mfma_f32_16x16x32_bf16 v[2:5], v[170:173], v[212:215], v[2:5]
	v_mfma_f32_16x16x32_bf16 v[54:57], v[166:169], v[182:185], v[54:57]
	v_mfma_f32_16x16x32_bf16 v[50:53], v[174:177], v[182:185], v[50:53]
	v_mfma_f32_16x16x32_bf16 v[38:41], v[166:169], v[190:193], v[38:41]
	v_mfma_f32_16x16x32_bf16 v[34:37], v[174:177], v[190:193], v[34:37]
	v_mfma_f32_16x16x32_bf16 v[22:25], v[166:169], v[208:211], v[22:25]
	v_mfma_f32_16x16x32_bf16 v[18:21], v[174:177], v[208:211], v[18:21]
	v_mfma_f32_16x16x32_bf16 v[6:9], v[166:169], v[216:219], v[6:9]
	v_mfma_f32_16x16x32_bf16 v[2:5], v[174:177], v[216:219], v[2:5]
	s_barrier
	s_setprio 0
	s_add_i32 s41, s41, 2
	s_add_u32 s39, s39, 0x100
	s_addc_u32 s40, s40, 0
	s_add_u32 s58, s58, 0x100
	s_addc_u32 s59, s59, 0
	s_cmp_gt_u32 s41, 13
	s_cbranch_scc0 .LBB0_647
	s_and_b64 vcc, exec, s[4:5]
	s_cbranch_vccz .LBB0_650
	s_barrier
